# adds lane-transposed, software-pipelined row stores for the in-projection diff-v and conv-GLU column tiles
# speedup vs baseline: 1.0023x; 1.0023x over previous
.LBB0_191:
	s_add_u32 s6, s4, 0xfffc0080
	s_addc_u32 s7, s5, -1
	s_add_i32 s53, 0, 0x10000
	s_cmp_eq_u32 s51, 12
	s_cselect_b32 s9, s15, s7
	s_cselect_b32 s8, s23, s6
	s_cselect_b32 s7, s17, s35
	s_cselect_b32 s6, s24, s25
	s_add_i32 s56, 0, 0x14000
	v_add_u32_e32 v116, s53, v185
	v_add_u32_e32 v152, s56, v185
	ds_read_b128 v[104:107], v116
	ds_read_b128 v[108:111], v116 offset:1024
	ds_read_b128 v[112:115], v116 offset:2048
	ds_read_b128 v[116:119], v116 offset:3072
	ds_read_b128 v[172:175], v152
	ds_read_b128 v[176:179], v152 offset:1024
	ds_read_b128 v[180:183], v152 offset:2048
	ds_read_b128 v[194:197], v152 offset:3072
	v_lshl_add_u64 v[154:155], s[4:5], 0, v[168:169]
	s_add_i32 m0, s29, 0xc000
	ds_read_b128 v[198:201], v192
	ds_read_b128 v[202:205], v192 offset:1024
	ds_read_b128 v[206:209], v192 offset:2048
	ds_read_b128 v[210:213], v192 offset:3072
	ds_read_b128 v[214:217], v192 offset:4096
	ds_read_b128 v[218:221], v192 offset:5120
	ds_read_b128 v[222:225], v192 offset:6144
	ds_read_b128 v[240:243], v192 offset:7168
	global_load_lds_dwordx4 v[154:155], off
	v_lshl_add_u64 v[154:155], s[4:5], 0, v[170:171]
	s_add_i32 m0, s29, 0xe000
	s_nop 0
	global_load_lds_dwordx4 v[154:155], off
	s_waitcnt vmcnt(8)
	s_waitcnt lgkmcnt(0)
	s_barrier
	s_setprio 1
	s_waitcnt lgkmcnt(0)
	v_mfma_f32_16x16x32_bf16 v[140:143], v[104:107], v[198:201], v[140:143]
	v_mfma_f32_16x16x32_bf16 v[136:139], v[112:115], v[198:201], v[136:139]
	v_mfma_f32_16x16x32_bf16 v[124:127], v[104:107], v[206:209], v[124:127]
	v_mfma_f32_16x16x32_bf16 v[120:123], v[112:115], v[206:209], v[120:123]
	v_mfma_f32_16x16x32_bf16 v[92:95], v[104:107], v[214:217], v[92:95]
	v_mfma_f32_16x16x32_bf16 v[88:91], v[112:115], v[214:217], v[88:91]
	v_mfma_f32_16x16x32_bf16 v[76:79], v[104:107], v[222:225], v[76:79]
	v_mfma_f32_16x16x32_bf16 v[72:75], v[112:115], v[222:225], v[72:75]
	v_mfma_f32_16x16x32_bf16 v[140:143], v[108:111], v[202:205], v[140:143]
	v_mfma_f32_16x16x32_bf16 v[136:139], v[116:119], v[202:205], v[136:139]
	v_mfma_f32_16x16x32_bf16 v[124:127], v[108:111], v[210:213], v[124:127]
	v_mfma_f32_16x16x32_bf16 v[120:123], v[116:119], v[210:213], v[120:123]
	v_mfma_f32_16x16x32_bf16 v[92:95], v[108:111], v[218:221], v[92:95]
	v_mfma_f32_16x16x32_bf16 v[88:91], v[116:119], v[218:221], v[88:91]
	v_mfma_f32_16x16x32_bf16 v[76:79], v[108:111], v[240:243], v[76:79]
	v_mfma_f32_16x16x32_bf16 v[72:75], v[116:119], v[240:243], v[72:75]
	s_setprio 0
	s_setprio 1
	v_mfma_f32_16x16x32_bf16 v[132:135], v[172:175], v[198:201], v[132:135]
	v_mfma_f32_16x16x32_bf16 v[128:131], v[180:183], v[198:201], v[128:131]
	v_mfma_f32_16x16x32_bf16 v[100:103], v[172:175], v[206:209], v[100:103]
	v_mfma_f32_16x16x32_bf16 v[96:99], v[180:183], v[206:209], v[96:99]
	v_mfma_f32_16x16x32_bf16 v[84:87], v[172:175], v[214:217], v[84:87]
	v_mfma_f32_16x16x32_bf16 v[80:83], v[180:183], v[214:217], v[80:83]
	v_mfma_f32_16x16x32_bf16 v[68:71], v[172:175], v[222:225], v[68:71]
	v_mfma_f32_16x16x32_bf16 v[64:67], v[180:183], v[222:225], v[64:67]
	v_mfma_f32_16x16x32_bf16 v[132:135], v[176:179], v[202:205], v[132:135]
	v_mfma_f32_16x16x32_bf16 v[128:131], v[194:197], v[202:205], v[128:131]
	v_mfma_f32_16x16x32_bf16 v[100:103], v[176:179], v[210:213], v[100:103]
	v_mfma_f32_16x16x32_bf16 v[96:99], v[194:197], v[210:213], v[96:99]
	v_mfma_f32_16x16x32_bf16 v[84:87], v[176:179], v[218:221], v[84:87]
	v_mfma_f32_16x16x32_bf16 v[80:83], v[194:197], v[218:221], v[80:83]
	v_mfma_f32_16x16x32_bf16 v[68:71], v[176:179], v[240:243], v[68:71]
	v_mfma_f32_16x16x32_bf16 v[64:67], v[194:197], v[240:243], v[64:67]
	s_setprio 0
	s_barrier
	s_add_i32 s53, s53, s28
	v_lshl_add_u64 v[154:155], s[6:7], 0, v[146:147]
	s_mov_b32 m0, s53
	ds_read_b128 v[198:201], v192 offset:16384
	ds_read_b128 v[202:205], v192 offset:17408
	ds_read_b128 v[206:209], v192 offset:18432
	ds_read_b128 v[210:213], v192 offset:19456
	ds_read_b128 v[214:217], v192 offset:20480
	ds_read_b128 v[218:221], v192 offset:21504
	ds_read_b128 v[222:225], v192 offset:22528
	ds_read_b128 v[240:243], v192 offset:23552
	global_load_lds_dwordx4 v[154:155], off
	s_add_i32 m0, s53, 0x2000
	s_add_u32 s54, s6, 0x40000
	v_lshl_add_u64 v[156:157], s[6:7], 0, v[150:151]
	s_addc_u32 s55, s7, 0
	s_add_i32 s53, s56, s28
	global_load_lds_dwordx4 v[156:157], off
	v_lshl_add_u64 v[158:159], s[54:55], 0, v[146:147]
	s_mov_b32 m0, s53
	v_lshl_add_u64 v[160:161], s[8:9], 0, v[148:149]
	global_load_lds_dwordx4 v[158:159], off
	v_lshl_add_u64 v[158:159], s[54:55], 0, v[150:151]
	s_add_i32 m0, s53, 0x2000
	s_nop 0
	global_load_lds_dwordx4 v[158:159], off
	v_lshl_add_u64 v[158:159], s[8:9], 0, v[144:145]
	s_mov_b32 m0, s29
	s_nop 0
	global_load_lds_dwordx4 v[158:159], off
	s_mov_b32 m0, s37
	s_nop 0
	global_load_lds_dwordx4 v[160:161], off
	s_waitcnt vmcnt(8)
	s_waitcnt lgkmcnt(0)
	s_barrier
	s_setprio 1
	s_waitcnt lgkmcnt(0)
	v_mfma_f32_16x16x32_bf16 v[60:63], v[104:107], v[198:201], v[60:63]
	v_mfma_f32_16x16x32_bf16 v[56:59], v[112:115], v[198:201], v[56:59]
	v_mfma_f32_16x16x32_bf16 v[44:47], v[104:107], v[206:209], v[44:47]
	v_mfma_f32_16x16x32_bf16 v[40:43], v[112:115], v[206:209], v[40:43]
	v_mfma_f32_16x16x32_bf16 v[28:31], v[104:107], v[214:217], v[28:31]
	v_mfma_f32_16x16x32_bf16 v[24:27], v[112:115], v[214:217], v[24:27]
	v_mfma_f32_16x16x32_bf16 v[12:15], v[104:107], v[222:225], v[12:15]
	v_mfma_f32_16x16x32_bf16 v[8:11], v[112:115], v[222:225], v[8:11]
	v_mfma_f32_16x16x32_bf16 v[60:63], v[108:111], v[202:205], v[60:63]
	v_mfma_f32_16x16x32_bf16 v[56:59], v[116:119], v[202:205], v[56:59]
	v_mfma_f32_16x16x32_bf16 v[44:47], v[108:111], v[210:213], v[44:47]
	v_mfma_f32_16x16x32_bf16 v[40:43], v[116:119], v[210:213], v[40:43]
	v_mfma_f32_16x16x32_bf16 v[28:31], v[108:111], v[218:221], v[28:31]
	v_mfma_f32_16x16x32_bf16 v[24:27], v[116:119], v[218:221], v[24:27]
	v_mfma_f32_16x16x32_bf16 v[12:15], v[108:111], v[240:243], v[12:15]
	v_mfma_f32_16x16x32_bf16 v[8:11], v[116:119], v[240:243], v[8:11]
	s_setprio 0
	s_setprio 1
	v_mfma_f32_16x16x32_bf16 v[52:55], v[172:175], v[198:201], v[52:55]
	v_mfma_f32_16x16x32_bf16 v[48:51], v[180:183], v[198:201], v[48:51]
	v_mfma_f32_16x16x32_bf16 v[36:39], v[172:175], v[206:209], v[36:39]
	v_mfma_f32_16x16x32_bf16 v[32:35], v[180:183], v[206:209], v[32:35]
	v_mfma_f32_16x16x32_bf16 v[20:23], v[172:175], v[214:217], v[20:23]
	v_mfma_f32_16x16x32_bf16 v[16:19], v[180:183], v[214:217], v[16:19]
	v_mfma_f32_16x16x32_bf16 v[4:7], v[172:175], v[222:225], v[4:7]
	v_mfma_f32_16x16x32_bf16 v[0:3], v[180:183], v[222:225], v[0:3]
	v_mfma_f32_16x16x32_bf16 v[52:55], v[176:179], v[202:205], v[52:55]
	v_mfma_f32_16x16x32_bf16 v[48:51], v[194:197], v[202:205], v[48:51]
	v_mfma_f32_16x16x32_bf16 v[36:39], v[176:179], v[210:213], v[36:39]
	v_mfma_f32_16x16x32_bf16 v[32:35], v[194:197], v[210:213], v[32:35]
	v_mfma_f32_16x16x32_bf16 v[20:23], v[176:179], v[218:221], v[20:23]
	v_mfma_f32_16x16x32_bf16 v[16:19], v[194:197], v[218:221], v[16:19]
	v_mfma_f32_16x16x32_bf16 v[4:7], v[176:179], v[240:243], v[4:7]
	v_mfma_f32_16x16x32_bf16 v[0:3], v[194:197], v[240:243], v[0:3]
	s_setprio 0
	s_barrier
	s_add_i32 s53, 0, 0x18000
	s_add_i32 s54, 0, 0x1c000
	v_add_u32_e32 v116, s53, v185
	v_add_u32_e32 v152, s54, v185
	ds_read_b128 v[104:107], v116
	ds_read_b128 v[108:111], v116 offset:1024
	ds_read_b128 v[112:115], v116 offset:2048
	ds_read_b128 v[116:119], v116 offset:3072
	ds_read_b128 v[172:175], v152
	ds_read_b128 v[176:179], v152 offset:1024
	ds_read_b128 v[180:183], v152 offset:2048
	ds_read_b128 v[194:197], v152 offset:3072
	s_add_u32 s8, s8, 0x40000
	s_addc_u32 s9, s9, 0
	s_mov_b32 m0, s39
	v_lshl_add_u64 v[226:227], s[8:9], 0, v[144:145]
	ds_read_b128 v[198:201], v192 offset:32768
	ds_read_b128 v[202:205], v192 offset:33792
	ds_read_b128 v[206:209], v192 offset:34816
	ds_read_b128 v[210:213], v192 offset:35840
	ds_read_b128 v[214:217], v192 offset:36864
	ds_read_b128 v[218:221], v192 offset:37888
	ds_read_b128 v[222:225], v192 offset:38912
	ds_read_b128 v[240:243], v192 offset:39936
	global_load_lds_dwordx4 v[226:227], off
	v_lshl_add_u64 v[226:227], s[8:9], 0, v[148:149]
	s_mov_b32 m0, s41
	s_nop 0
	global_load_lds_dwordx4 v[226:227], off
	s_waitcnt vmcnt(8)
	s_waitcnt lgkmcnt(0)
	s_barrier
	s_setprio 1
	s_waitcnt lgkmcnt(0)
	v_mfma_f32_16x16x32_bf16 v[140:143], v[104:107], v[198:201], v[140:143]
	v_mfma_f32_16x16x32_bf16 v[136:139], v[112:115], v[198:201], v[136:139]
	v_mfma_f32_16x16x32_bf16 v[124:127], v[104:107], v[206:209], v[124:127]
	v_mfma_f32_16x16x32_bf16 v[120:123], v[112:115], v[206:209], v[120:123]
	v_mfma_f32_16x16x32_bf16 v[92:95], v[104:107], v[214:217], v[92:95]
	v_mfma_f32_16x16x32_bf16 v[88:91], v[112:115], v[214:217], v[88:91]
	v_mfma_f32_16x16x32_bf16 v[76:79], v[104:107], v[222:225], v[76:79]
	v_mfma_f32_16x16x32_bf16 v[72:75], v[112:115], v[222:225], v[72:75]
	v_mfma_f32_16x16x32_bf16 v[140:143], v[108:111], v[202:205], v[140:143]
	v_mfma_f32_16x16x32_bf16 v[136:139], v[116:119], v[202:205], v[136:139]
	v_mfma_f32_16x16x32_bf16 v[124:127], v[108:111], v[210:213], v[124:127]
	v_mfma_f32_16x16x32_bf16 v[120:123], v[116:119], v[210:213], v[120:123]
	v_mfma_f32_16x16x32_bf16 v[92:95], v[108:111], v[218:221], v[92:95]
	v_mfma_f32_16x16x32_bf16 v[88:91], v[116:119], v[218:221], v[88:91]
	v_mfma_f32_16x16x32_bf16 v[76:79], v[108:111], v[240:243], v[76:79]
	v_mfma_f32_16x16x32_bf16 v[72:75], v[116:119], v[240:243], v[72:75]
	s_setprio 0
	s_setprio 1
	v_mfma_f32_16x16x32_bf16 v[132:135], v[172:175], v[198:201], v[132:135]
	v_mfma_f32_16x16x32_bf16 v[128:131], v[180:183], v[198:201], v[128:131]
	v_mfma_f32_16x16x32_bf16 v[100:103], v[172:175], v[206:209], v[100:103]
	v_mfma_f32_16x16x32_bf16 v[96:99], v[180:183], v[206:209], v[96:99]
	v_mfma_f32_16x16x32_bf16 v[84:87], v[172:175], v[214:217], v[84:87]
	v_mfma_f32_16x16x32_bf16 v[80:83], v[180:183], v[214:217], v[80:83]
	v_mfma_f32_16x16x32_bf16 v[68:71], v[172:175], v[222:225], v[68:71]
	v_mfma_f32_16x16x32_bf16 v[64:67], v[180:183], v[222:225], v[64:67]
	v_mfma_f32_16x16x32_bf16 v[132:135], v[176:179], v[202:205], v[132:135]
	v_mfma_f32_16x16x32_bf16 v[128:131], v[194:197], v[202:205], v[128:131]
	v_mfma_f32_16x16x32_bf16 v[100:103], v[176:179], v[210:213], v[100:103]
	v_mfma_f32_16x16x32_bf16 v[96:99], v[194:197], v[210:213], v[96:99]
	v_mfma_f32_16x16x32_bf16 v[84:87], v[176:179], v[218:221], v[84:87]
	v_mfma_f32_16x16x32_bf16 v[80:83], v[194:197], v[218:221], v[80:83]
	v_mfma_f32_16x16x32_bf16 v[68:71], v[176:179], v[240:243], v[68:71]
	v_mfma_f32_16x16x32_bf16 v[64:67], v[194:197], v[240:243], v[64:67]
	s_setprio 0
	s_barrier
	s_add_i32 s8, s53, s28
	v_lshl_add_u64 v[154:155], v[154:155], 0, s[44:45]
	s_mov_b32 m0, s8
	ds_read_b128 v[198:201], v192 offset:49152
	ds_read_b128 v[202:205], v192 offset:50176
	ds_read_b128 v[206:209], v192 offset:51200
	ds_read_b128 v[210:213], v192 offset:52224
	ds_read_b128 v[214:217], v192 offset:53248
	ds_read_b128 v[218:221], v192 offset:54272
	ds_read_b128 v[222:225], v192 offset:55296
	ds_read_b128 v[240:243], v192 offset:56320
	global_load_lds_dwordx4 v[154:155], off
	s_add_i32 m0, s8, 0x2000
	s_add_u32 s6, s6, 0x40080
	v_lshl_add_u64 v[154:155], v[156:157], 0, s[44:45]
	s_addc_u32 s7, s7, 0
	s_add_i32 s8, s54, s28
	global_load_lds_dwordx4 v[154:155], off
	v_lshl_add_u64 v[154:155], s[6:7], 0, v[146:147]
	s_mov_b32 m0, s8
	s_nop 0
	global_load_lds_dwordx4 v[154:155], off
	v_lshl_add_u64 v[154:155], s[6:7], 0, v[150:151]
	s_add_i32 m0, s8, 0x2000
	s_nop 0
	global_load_lds_dwordx4 v[154:155], off
	v_lshl_add_u64 v[154:155], v[158:159], 0, s[44:45]
	s_mov_b32 m0, s46
	s_nop 0
	global_load_lds_dwordx4 v[154:155], off
	v_lshl_add_u64 v[154:155], v[160:161], 0, s[44:45]
	s_mov_b32 m0, s47
	s_nop 0
	global_load_lds_dwordx4 v[154:155], off
	s_waitcnt vmcnt(8)
	s_waitcnt lgkmcnt(0)
	s_barrier
	s_setprio 1
	s_waitcnt lgkmcnt(0)
	v_mfma_f32_16x16x32_bf16 v[60:63], v[104:107], v[198:201], v[60:63]
	v_mfma_f32_16x16x32_bf16 v[56:59], v[112:115], v[198:201], v[56:59]
	v_mfma_f32_16x16x32_bf16 v[44:47], v[104:107], v[206:209], v[44:47]
	v_mfma_f32_16x16x32_bf16 v[40:43], v[112:115], v[206:209], v[40:43]
	v_mfma_f32_16x16x32_bf16 v[28:31], v[104:107], v[214:217], v[28:31]
	v_mfma_f32_16x16x32_bf16 v[24:27], v[112:115], v[214:217], v[24:27]
	v_mfma_f32_16x16x32_bf16 v[12:15], v[104:107], v[222:225], v[12:15]
	v_mfma_f32_16x16x32_bf16 v[8:11], v[112:115], v[222:225], v[8:11]
	v_mfma_f32_16x16x32_bf16 v[60:63], v[108:111], v[202:205], v[60:63]
	v_mfma_f32_16x16x32_bf16 v[56:59], v[116:119], v[202:205], v[56:59]
	v_mfma_f32_16x16x32_bf16 v[44:47], v[108:111], v[210:213], v[44:47]
	v_mfma_f32_16x16x32_bf16 v[40:43], v[116:119], v[210:213], v[40:43]
	v_mfma_f32_16x16x32_bf16 v[28:31], v[108:111], v[218:221], v[28:31]
	v_mfma_f32_16x16x32_bf16 v[24:27], v[116:119], v[218:221], v[24:27]
	v_mfma_f32_16x16x32_bf16 v[12:15], v[108:111], v[240:243], v[12:15]
	v_mfma_f32_16x16x32_bf16 v[8:11], v[116:119], v[240:243], v[8:11]
	s_setprio 0
	s_setprio 1
	v_mfma_f32_16x16x32_bf16 v[52:55], v[172:175], v[198:201], v[52:55]
	v_mfma_f32_16x16x32_bf16 v[48:51], v[180:183], v[198:201], v[48:51]
	v_mfma_f32_16x16x32_bf16 v[36:39], v[172:175], v[206:209], v[36:39]
	v_mfma_f32_16x16x32_bf16 v[32:35], v[180:183], v[206:209], v[32:35]
	v_mfma_f32_16x16x32_bf16 v[20:23], v[172:175], v[214:217], v[20:23]
	v_mfma_f32_16x16x32_bf16 v[16:19], v[180:183], v[214:217], v[16:19]
	v_mfma_f32_16x16x32_bf16 v[4:7], v[172:175], v[222:225], v[4:7]
	v_mfma_f32_16x16x32_bf16 v[0:3], v[180:183], v[222:225], v[0:3]
	v_mfma_f32_16x16x32_bf16 v[52:55], v[176:179], v[202:205], v[52:55]
	v_mfma_f32_16x16x32_bf16 v[48:51], v[194:197], v[202:205], v[48:51]
	v_mfma_f32_16x16x32_bf16 v[36:39], v[176:179], v[210:213], v[36:39]
	v_mfma_f32_16x16x32_bf16 v[32:35], v[194:197], v[210:213], v[32:35]
	v_mfma_f32_16x16x32_bf16 v[20:23], v[176:179], v[218:221], v[20:23]
	v_mfma_f32_16x16x32_bf16 v[16:19], v[194:197], v[218:221], v[16:19]
	v_mfma_f32_16x16x32_bf16 v[4:7], v[176:179], v[240:243], v[4:7]
	v_mfma_f32_16x16x32_bf16 v[0:3], v[194:197], v[240:243], v[0:3]
	s_setprio 0
	s_barrier
	s_add_i32 s51, s51, 2
	s_add_u32 s4, s4, 0x100
	s_addc_u32 s5, s5, 0
	s_add_u32 s25, s25, 0x100
	s_addc_u32 s35, s35, 0
	s_cmp_gt_u32 s51, 13
	s_cbranch_scc0 .LBB0_191
	v_mbcnt_lo_u32_b32 v194, -1, 0
	v_mbcnt_hi_u32_b32 v194, -1, v194
	v_and_b32_e32 v198, 15, v194
	v_lshrrev_b32_e32 v199, 2, v194
	v_sub_u32_e32 v196, v199, v198
	v_mul_i32_i24_e32 v196, 0x1800, v196
	v_and_b32_e32 v198, 3, v194
	v_lshrrev_b32_e32 v197, 4, v194
	v_sub_u32_e32 v197, v198, v197
	v_lshl_add_u32 v196, v197, 4, v196
	v_ashrrev_i32_e32 v197, 31, v196
	v_lshl_add_u32 v194, v198, 4, v199
	v_lshlrev_b32_e32 v194, 2, v194
	s_and_b64 vcc, exec, s[12:13]
	s_cbranch_vccz .LBB0_194
	s_barrier

.LBB0_199:
	s_cmp_gt_u32 s40, 9
	s_cbranch_scc0 .LBB0_201
	v_mul_f32_e32 v104, 0xbfb8aa3b, v180
	v_exp_f32_e32 v106, v104
	v_mul_f32_e32 v104, 0xbfb8aa3b, v181
	v_mul_f32_e32 v108, 0xbfb8aa3b, v178
	v_exp_f32_e32 v107, v104
	v_exp_f32_e32 v109, v108
	v_mul_f32_e32 v108, 0xbfb8aa3b, v179
	v_exp_f32_e32 v110, v108
	v_add_f32_e32 v107, 1.0, v107
	v_mul_f32_e32 v111, 0xbfb8aa3b, v177
	v_mul_f32_e32 v112, 0xbfb8aa3b, v174
	v_rcp_f32_e32 v108, v107
	v_add_f32_e32 v107, 1.0, v109
	v_add_f32_e32 v109, 1.0, v110
	v_mul_f32_e32 v110, 0xbfb8aa3b, v176
	v_exp_f32_e32 v111, v111
	v_exp_f32_e32 v113, v112
	v_mul_f32_e32 v112, 0xbfb8aa3b, v175
	v_exp_f32_e32 v110, v110
	v_exp_f32_e32 v114, v112
	v_add_f32_e32 v106, 1.0, v106
	v_rcp_f32_e32 v106, v106
	v_rcp_f32_e32 v107, v107
	v_add_f32_e32 v111, 1.0, v111
	v_mov_b64_e32 v[68:69], s[70:71]
	v_rcp_f32_e32 v109, v109
	v_add_f32_e32 v110, 1.0, v110
	v_rcp_f32_e32 v112, v111
	v_add_f32_e32 v111, 1.0, v113
	v_add_f32_e32 v113, 1.0, v114
	v_lshlrev_b32_e32 v114, 1, v186
	v_mad_i64_i32 v[104:105], s[6:7], v172, s60, v[68:69]
	v_rcp_f32_e32 v110, v110
	v_rcp_f32_e32 v111, v111
	v_lshl_or_b32 v152, s40, 8, v114
	v_rcp_f32_e32 v113, v113
	v_lshl_add_u64 v[114:115], v[104:105], 0, v[152:153]
	v_mov_b32_e32 v104, v140
	v_mov_b32_e32 v105, v142
	v_pk_mul_f32 v[104:105], v[104:105], v[106:107]
	v_mov_b32_e32 v106, v141
	v_mov_b32_e32 v107, v143
	v_pk_mul_f32 v[106:107], v[106:107], v[108:109]
	v_mov_b32_e32 v108, v136
	v_mov_b32_e32 v109, v138
	v_pk_mul_f32 v[108:109], v[108:109], v[110:111]
	v_mov_b32_e32 v110, v137
	v_mov_b32_e32 v111, v139
	v_pk_mul_f32 v[110:111], v[110:111], v[112:113]
	v_bfe_u32 v116, v107, 16, 1
	v_bfe_u32 v112, v111, 16, 1
	v_bfe_u32 v113, v110, 16, 1
	v_bfe_u32 v117, v106, 16, 1
	v_add3_u32 v117, v106, v117, s96
	v_add3_u32 v116, v107, v116, s96
	v_add3_u32 v106, v110, v113, s96
	v_add3_u32 v107, v111, v112, s96
	v_bfe_u32 v110, v104, 16, 1
	v_bfe_u32 v111, v105, 16, 1
	v_bfe_u32 v112, v108, 16, 1
	v_bfe_u32 v113, v109, 16, 1
	v_add3_u32 v109, v109, v113, s96
	v_add3_u32 v108, v108, v112, s96
	v_add3_u32 v105, v105, v111, s96
	v_add3_u32 v104, v104, v110, s96
	v_lshrrev_b32_e32 v104, 16, v104
	v_lshrrev_b32_e32 v105, 16, v105
	v_lshrrev_b32_e32 v108, 16, v108
	v_lshrrev_b32_e32 v109, 16, v109
	v_and_or_b32 v107, v107, s97, v109
	v_and_or_b32 v106, v106, s97, v108
	v_and_or_b32 v105, v116, s97, v105
	v_and_or_b32 v104, v117, s97, v104
	ds_bpermute_b32 v208, v194, v104
	ds_bpermute_b32 v209, v194, v105
	ds_bpermute_b32 v210, v194, v106
	ds_bpermute_b32 v211, v194, v107
	v_lshl_add_u64 v[198:199], v[114:115], 0, v[196:197]
	v_mul_f32_e32 v108, 0xbfb8aa3b, v132
	v_exp_f32_e32 v109, v108
	v_mul_f32_e32 v104, 0xbfb8aa3b, v134
	v_exp_f32_e32 v106, v104
	v_mul_f32_e32 v104, 0xbfb8aa3b, v135
	v_exp_f32_e32 v107, v104
	v_mul_f32_e32 v108, 0xbfb8aa3b, v133
	v_exp_f32_e32 v110, v108
	v_mul_f32_e32 v111, 0xbfb8aa3b, v131
	v_add_f32_e32 v107, 1.0, v107
	v_rcp_f32_e32 v108, v107
	v_add_f32_e32 v107, 1.0, v109
	v_add_f32_e32 v109, 1.0, v110
	v_mul_f32_e32 v110, 0xbfb8aa3b, v130
	v_exp_f32_e32 v111, v111
	v_mul_f32_e32 v112, 0xbfb8aa3b, v102
	v_exp_f32_e32 v110, v110
	v_exp_f32_e32 v113, v112
	v_mul_f32_e32 v112, 0xbfb8aa3b, v103
	v_exp_f32_e32 v114, v112
	v_add_f32_e32 v106, 1.0, v106
	v_rcp_f32_e32 v106, v106
	v_rcp_f32_e32 v107, v107
	v_add_f32_e32 v111, 1.0, v111
	v_rcp_f32_e32 v109, v109
	v_add_f32_e32 v110, 1.0, v110
	v_rcp_f32_e32 v112, v111
	v_add_f32_e32 v111, 1.0, v113
	v_mad_i64_i32 v[104:105], s[6:7], v128, s60, v[68:69]
	v_rcp_f32_e32 v110, v110
	v_rcp_f32_e32 v111, v111
	v_add_f32_e32 v113, 1.0, v114
	v_rcp_f32_e32 v113, v113
	v_lshl_add_u64 v[114:115], v[104:105], 0, v[152:153]
	v_mov_b32_e32 v104, v124
	v_mov_b32_e32 v105, v126
	v_pk_mul_f32 v[104:105], v[104:105], v[106:107]
	v_mov_b32_e32 v106, v125
	v_mov_b32_e32 v107, v127
	v_pk_mul_f32 v[106:107], v[106:107], v[108:109]
	v_mov_b32_e32 v108, v120
	v_mov_b32_e32 v109, v122
	v_pk_mul_f32 v[108:109], v[108:109], v[110:111]
	v_mov_b32_e32 v110, v121
	v_mov_b32_e32 v111, v123
	v_pk_mul_f32 v[110:111], v[110:111], v[112:113]
	v_bfe_u32 v116, v107, 16, 1
	v_bfe_u32 v112, v111, 16, 1
	v_bfe_u32 v113, v110, 16, 1
	v_bfe_u32 v117, v106, 16, 1
	v_add3_u32 v117, v106, v117, s96
	v_add3_u32 v116, v107, v116, s96
	v_add3_u32 v106, v110, v113, s96
	v_add3_u32 v107, v111, v112, s96
	v_bfe_u32 v110, v104, 16, 1
	v_bfe_u32 v111, v105, 16, 1
	v_bfe_u32 v112, v108, 16, 1
	v_bfe_u32 v113, v109, 16, 1
	v_add3_u32 v109, v109, v113, s96
	v_add3_u32 v108, v108, v112, s96
	v_add3_u32 v105, v105, v111, s96
	v_add3_u32 v104, v104, v110, s96
	v_lshrrev_b32_e32 v104, 16, v104
	v_lshrrev_b32_e32 v105, 16, v105
	v_lshrrev_b32_e32 v108, 16, v108
	v_lshrrev_b32_e32 v109, 16, v109
	v_and_or_b32 v107, v107, s97, v109
	v_and_or_b32 v106, v106, s97, v108
	v_and_or_b32 v105, v116, s97, v105
	v_and_or_b32 v104, v117, s97, v104
	s_waitcnt lgkmcnt(0)
	global_store_dwordx4 v[198:199], v[208:211], off offset:2560
	ds_bpermute_b32 v216, v194, v104
	ds_bpermute_b32 v217, v194, v105
	ds_bpermute_b32 v218, v194, v106
	ds_bpermute_b32 v219, v194, v107
	v_lshl_add_u64 v[240:241], v[114:115], 0, v[196:197]
	v_mul_f32_e32 v108, 0xbfb8aa3b, v98
	v_exp_f32_e32 v109, v108
	v_mul_f32_e32 v104, 0xbfb8aa3b, v100
	v_exp_f32_e32 v106, v104
	v_mul_f32_e32 v104, 0xbfb8aa3b, v101
	v_exp_f32_e32 v107, v104
	v_mul_f32_e32 v108, 0xbfb8aa3b, v99
	v_exp_f32_e32 v110, v108
	v_mul_f32_e32 v111, 0xbfb8aa3b, v87
	v_add_f32_e32 v107, 1.0, v107
	v_rcp_f32_e32 v108, v107
	v_add_f32_e32 v107, 1.0, v109
	v_add_f32_e32 v109, 1.0, v110
	v_mul_f32_e32 v110, 0xbfb8aa3b, v86
	v_exp_f32_e32 v111, v111
	v_mul_f32_e32 v112, 0xbfb8aa3b, v84
	v_exp_f32_e32 v110, v110
	v_exp_f32_e32 v113, v112
	v_mul_f32_e32 v112, 0xbfb8aa3b, v85
	v_exp_f32_e32 v114, v112
	v_add_f32_e32 v106, 1.0, v106
	v_rcp_f32_e32 v106, v106
	v_rcp_f32_e32 v107, v107
	v_add_f32_e32 v111, 1.0, v111
	v_rcp_f32_e32 v109, v109
	v_add_f32_e32 v110, 1.0, v110
	v_rcp_f32_e32 v112, v111
	v_add_f32_e32 v111, 1.0, v113
	v_mad_i64_i32 v[104:105], s[6:7], v96, s60, v[68:69]
	v_rcp_f32_e32 v110, v110
	v_rcp_f32_e32 v111, v111
	v_add_f32_e32 v113, 1.0, v114
	v_rcp_f32_e32 v113, v113
	v_lshl_add_u64 v[114:115], v[104:105], 0, v[152:153]
	v_mov_b32_e32 v104, v92
	v_mov_b32_e32 v105, v94
	v_pk_mul_f32 v[104:105], v[104:105], v[106:107]
	v_mov_b32_e32 v106, v93
	v_mov_b32_e32 v107, v95
	v_pk_mul_f32 v[106:107], v[106:107], v[108:109]
	v_mov_b32_e32 v108, v88
	v_mov_b32_e32 v109, v90
	v_pk_mul_f32 v[108:109], v[108:109], v[110:111]
	v_mov_b32_e32 v110, v89
	v_mov_b32_e32 v111, v91
	v_pk_mul_f32 v[110:111], v[110:111], v[112:113]
	v_bfe_u32 v116, v107, 16, 1
	v_bfe_u32 v112, v111, 16, 1
	v_bfe_u32 v113, v110, 16, 1
	v_bfe_u32 v117, v106, 16, 1
	v_add3_u32 v117, v106, v117, s96
	v_add3_u32 v116, v107, v116, s96
	v_add3_u32 v106, v110, v113, s96
	v_add3_u32 v107, v111, v112, s96
	v_bfe_u32 v110, v104, 16, 1
	v_bfe_u32 v111, v105, 16, 1
	v_bfe_u32 v112, v108, 16, 1
	v_bfe_u32 v113, v109, 16, 1
	v_add3_u32 v109, v109, v113, s96
	v_add3_u32 v108, v108, v112, s96
	v_add3_u32 v105, v105, v111, s96
	v_add3_u32 v104, v104, v110, s96
	v_lshrrev_b32_e32 v104, 16, v104
	v_lshrrev_b32_e32 v105, 16, v105
	v_lshrrev_b32_e32 v108, 16, v108
	v_lshrrev_b32_e32 v109, 16, v109
	v_and_or_b32 v107, v107, s97, v109
	v_and_or_b32 v106, v106, s97, v108
	v_and_or_b32 v105, v116, s97, v105
	v_and_or_b32 v104, v117, s97, v104
	s_waitcnt lgkmcnt(0)
	global_store_dwordx4 v[240:241], v[216:219], off offset:2560
	ds_bpermute_b32 v208, v194, v104
	ds_bpermute_b32 v209, v194, v105
	ds_bpermute_b32 v210, v194, v106
	ds_bpermute_b32 v211, v194, v107
	v_lshl_add_u64 v[198:199], v[114:115], 0, v[196:197]
	v_mul_f32_e32 v108, 0xbfb8aa3b, v70
	v_exp_f32_e32 v109, v108
	v_mul_f32_e32 v104, 0xbfb8aa3b, v82
	v_exp_f32_e32 v106, v104
	v_mul_f32_e32 v104, 0xbfb8aa3b, v83
	v_exp_f32_e32 v107, v104
	v_mul_f32_e32 v108, 0xbfb8aa3b, v71
	v_exp_f32_e32 v110, v108
	v_mul_f32_e32 v111, 0xbfb8aa3b, v65
	v_add_f32_e32 v107, 1.0, v107
	v_rcp_f32_e32 v108, v107
	v_add_f32_e32 v107, 1.0, v109
	v_add_f32_e32 v109, 1.0, v110
	v_mul_f32_e32 v110, 0xbfb8aa3b, v64
	v_exp_f32_e32 v111, v111
	v_mul_f32_e32 v112, 0xbfb8aa3b, v66
	v_exp_f32_e32 v110, v110
	v_exp_f32_e32 v113, v112
	v_mul_f32_e32 v112, 0xbfb8aa3b, v67
	v_exp_f32_e32 v114, v112
	v_add_f32_e32 v106, 1.0, v106
	v_rcp_f32_e32 v106, v106
	v_rcp_f32_e32 v107, v107
	v_add_f32_e32 v111, 1.0, v111
	v_rcp_f32_e32 v109, v109
	v_add_f32_e32 v110, 1.0, v110
	v_rcp_f32_e32 v112, v111
	v_add_f32_e32 v111, 1.0, v113
	v_mad_i64_i32 v[104:105], s[6:7], v80, s60, v[68:69]
	v_rcp_f32_e32 v110, v110
	v_rcp_f32_e32 v111, v111
	v_add_f32_e32 v113, 1.0, v114
	v_rcp_f32_e32 v113, v113
	v_lshl_add_u64 v[114:115], v[104:105], 0, v[152:153]
	v_mov_b32_e32 v104, v76
	v_mov_b32_e32 v105, v78
	v_pk_mul_f32 v[104:105], v[104:105], v[106:107]
	v_mov_b32_e32 v106, v77
	v_mov_b32_e32 v107, v79
	v_pk_mul_f32 v[106:107], v[106:107], v[108:109]
	v_mov_b32_e32 v108, v72
	v_mov_b32_e32 v109, v74
	v_pk_mul_f32 v[108:109], v[108:109], v[110:111]
	v_mov_b32_e32 v110, v73
	v_mov_b32_e32 v111, v75
	v_pk_mul_f32 v[110:111], v[110:111], v[112:113]
	v_bfe_u32 v116, v107, 16, 1
	v_bfe_u32 v112, v111, 16, 1
	v_bfe_u32 v113, v110, 16, 1
	v_bfe_u32 v117, v106, 16, 1
	v_add3_u32 v117, v106, v117, s96
	v_add3_u32 v116, v107, v116, s96
	v_add3_u32 v106, v110, v113, s96
	v_add3_u32 v107, v111, v112, s96
	v_bfe_u32 v110, v104, 16, 1
	v_bfe_u32 v111, v105, 16, 1
	v_bfe_u32 v112, v108, 16, 1
	v_bfe_u32 v113, v109, 16, 1
	v_add3_u32 v109, v109, v113, s96
	v_add3_u32 v108, v108, v112, s96
	v_add3_u32 v105, v105, v111, s96
	v_add3_u32 v104, v104, v110, s96
	v_lshrrev_b32_e32 v104, 16, v104
	v_lshrrev_b32_e32 v105, 16, v105
	v_lshrrev_b32_e32 v108, 16, v108
	v_lshrrev_b32_e32 v109, 16, v109
	v_and_or_b32 v107, v107, s97, v109
	v_and_or_b32 v106, v106, s97, v108
	v_and_or_b32 v105, v116, s97, v105
	v_and_or_b32 v104, v117, s97, v104
	s_waitcnt lgkmcnt(0)
	global_store_dwordx4 v[198:199], v[208:211], off offset:2560
	ds_bpermute_b32 v216, v194, v104
	ds_bpermute_b32 v217, v194, v105
	ds_bpermute_b32 v218, v194, v106
	ds_bpermute_b32 v219, v194, v107
	v_lshl_add_u64 v[240:241], v[114:115], 0, v[196:197]
	v_mul_f32_e32 v108, 0xbfb8aa3b, v54
	v_exp_f32_e32 v109, v108
	v_mul_f32_e32 v104, 0xbfb8aa3b, v52
	v_exp_f32_e32 v106, v104
	v_mul_f32_e32 v104, 0xbfb8aa3b, v53
	v_exp_f32_e32 v107, v104
	v_mul_f32_e32 v108, 0xbfb8aa3b, v55
	v_exp_f32_e32 v110, v108
	v_mul_f32_e32 v111, 0xbfb8aa3b, v49
	v_add_f32_e32 v107, 1.0, v107
	v_rcp_f32_e32 v108, v107
	v_add_f32_e32 v107, 1.0, v109
	v_add_f32_e32 v109, 1.0, v110
	v_mul_f32_e32 v110, 0xbfb8aa3b, v48
	v_exp_f32_e32 v111, v111
	v_mul_f32_e32 v112, 0xbfb8aa3b, v50
	v_exp_f32_e32 v110, v110
	v_exp_f32_e32 v113, v112
	v_mul_f32_e32 v112, 0xbfb8aa3b, v51
	v_exp_f32_e32 v114, v112
	v_add_f32_e32 v106, 1.0, v106
	v_rcp_f32_e32 v106, v106
	v_rcp_f32_e32 v107, v107
	v_add_f32_e32 v111, 1.0, v111
	v_rcp_f32_e32 v109, v109
	v_add_f32_e32 v110, 1.0, v110
	v_rcp_f32_e32 v112, v111
	v_add_f32_e32 v111, 1.0, v113
	v_mad_i64_i32 v[104:105], s[6:7], v173, s60, v[68:69]
	v_rcp_f32_e32 v110, v110
	v_rcp_f32_e32 v111, v111
	v_add_f32_e32 v113, 1.0, v114
	v_rcp_f32_e32 v113, v113
	v_lshl_add_u64 v[114:115], v[104:105], 0, v[152:153]
	v_mov_b32_e32 v104, v60
	v_mov_b32_e32 v105, v62
	v_pk_mul_f32 v[104:105], v[104:105], v[106:107]
	v_mov_b32_e32 v106, v61
	v_mov_b32_e32 v107, v63
	v_pk_mul_f32 v[106:107], v[106:107], v[108:109]
	v_mov_b32_e32 v108, v56
	v_mov_b32_e32 v109, v58
	v_pk_mul_f32 v[108:109], v[108:109], v[110:111]
	v_mov_b32_e32 v110, v57
	v_mov_b32_e32 v111, v59
	v_pk_mul_f32 v[110:111], v[110:111], v[112:113]
	v_bfe_u32 v116, v107, 16, 1
	v_bfe_u32 v112, v111, 16, 1
	v_bfe_u32 v113, v110, 16, 1
	v_bfe_u32 v117, v106, 16, 1
	v_add3_u32 v117, v106, v117, s96
	v_add3_u32 v116, v107, v116, s96
	v_add3_u32 v106, v110, v113, s96
	v_add3_u32 v107, v111, v112, s96
	v_bfe_u32 v110, v104, 16, 1
	v_bfe_u32 v111, v105, 16, 1
	v_bfe_u32 v112, v108, 16, 1
	v_bfe_u32 v113, v109, 16, 1
	v_add3_u32 v109, v109, v113, s96
	v_add3_u32 v108, v108, v112, s96
	v_add3_u32 v105, v105, v111, s96
	v_add3_u32 v104, v104, v110, s96
	v_lshrrev_b32_e32 v104, 16, v104
	v_lshrrev_b32_e32 v105, 16, v105
	v_lshrrev_b32_e32 v108, 16, v108
	v_lshrrev_b32_e32 v109, 16, v109
	v_and_or_b32 v107, v107, s97, v109
	v_and_or_b32 v106, v106, s97, v108
	v_and_or_b32 v105, v116, s97, v105
	v_and_or_b32 v104, v117, s97, v104
	s_waitcnt lgkmcnt(0)
	global_store_dwordx4 v[240:241], v[216:219], off offset:2560
	ds_bpermute_b32 v208, v194, v104
	ds_bpermute_b32 v209, v194, v105
	ds_bpermute_b32 v210, v194, v106
	ds_bpermute_b32 v211, v194, v107
	v_lshl_add_u64 v[198:199], v[114:115], 0, v[196:197]
	v_mul_f32_e32 v108, 0xbfb8aa3b, v38
	v_exp_f32_e32 v109, v108
	v_mul_f32_e32 v104, 0xbfb8aa3b, v36
	v_exp_f32_e32 v106, v104
	v_mul_f32_e32 v104, 0xbfb8aa3b, v37
	v_exp_f32_e32 v107, v104
	v_mul_f32_e32 v108, 0xbfb8aa3b, v39
	v_exp_f32_e32 v110, v108
	v_mul_f32_e32 v111, 0xbfb8aa3b, v33
	v_add_f32_e32 v107, 1.0, v107
	v_rcp_f32_e32 v108, v107
	v_add_f32_e32 v107, 1.0, v109
	v_add_f32_e32 v109, 1.0, v110
	v_mul_f32_e32 v110, 0xbfb8aa3b, v32
	v_exp_f32_e32 v111, v111
	v_mul_f32_e32 v112, 0xbfb8aa3b, v34
	v_exp_f32_e32 v110, v110
	v_exp_f32_e32 v113, v112
	v_mul_f32_e32 v112, 0xbfb8aa3b, v35
	v_exp_f32_e32 v114, v112
	v_add_f32_e32 v106, 1.0, v106
	v_rcp_f32_e32 v106, v106
	v_rcp_f32_e32 v107, v107
	v_add_f32_e32 v111, 1.0, v111
	v_rcp_f32_e32 v109, v109
	v_add_f32_e32 v110, 1.0, v110
	v_rcp_f32_e32 v112, v111
	v_add_f32_e32 v111, 1.0, v113
	v_mad_i64_i32 v[104:105], s[6:7], v129, s60, v[68:69]
	v_rcp_f32_e32 v110, v110
	v_rcp_f32_e32 v111, v111
	v_add_f32_e32 v113, 1.0, v114
	v_rcp_f32_e32 v113, v113
	v_lshl_add_u64 v[114:115], v[104:105], 0, v[152:153]
	v_mov_b32_e32 v104, v44
	v_mov_b32_e32 v105, v46
	v_pk_mul_f32 v[104:105], v[104:105], v[106:107]
	v_mov_b32_e32 v106, v45
	v_mov_b32_e32 v107, v47
	v_pk_mul_f32 v[106:107], v[106:107], v[108:109]
	v_mov_b32_e32 v108, v40
	v_mov_b32_e32 v109, v42
	v_pk_mul_f32 v[108:109], v[108:109], v[110:111]
	v_mov_b32_e32 v110, v41
	v_mov_b32_e32 v111, v43
	v_pk_mul_f32 v[110:111], v[110:111], v[112:113]
	v_bfe_u32 v116, v107, 16, 1
	v_bfe_u32 v112, v111, 16, 1
	v_bfe_u32 v113, v110, 16, 1
	v_bfe_u32 v117, v106, 16, 1
	v_add3_u32 v117, v106, v117, s96
	v_add3_u32 v116, v107, v116, s96
	v_add3_u32 v106, v110, v113, s96
	v_add3_u32 v107, v111, v112, s96
	v_bfe_u32 v110, v104, 16, 1
	v_bfe_u32 v111, v105, 16, 1
	v_bfe_u32 v112, v108, 16, 1
	v_bfe_u32 v113, v109, 16, 1
	v_add3_u32 v109, v109, v113, s96
	v_add3_u32 v108, v108, v112, s96
	v_add3_u32 v105, v105, v111, s96
	v_add3_u32 v104, v104, v110, s96
	v_lshrrev_b32_e32 v104, 16, v104
	v_lshrrev_b32_e32 v105, 16, v105
	v_lshrrev_b32_e32 v108, 16, v108
	v_lshrrev_b32_e32 v109, 16, v109
	v_and_or_b32 v107, v107, s97, v109
	v_and_or_b32 v106, v106, s97, v108
	v_and_or_b32 v105, v116, s97, v105
	v_and_or_b32 v104, v117, s97, v104
	s_waitcnt lgkmcnt(0)
	global_store_dwordx4 v[198:199], v[208:211], off offset:2560
	ds_bpermute_b32 v216, v194, v104
	ds_bpermute_b32 v217, v194, v105
	ds_bpermute_b32 v218, v194, v106
	ds_bpermute_b32 v219, v194, v107
	v_lshl_add_u64 v[240:241], v[114:115], 0, v[196:197]
	v_mul_f32_e32 v108, 0xbfb8aa3b, v22
	v_exp_f32_e32 v109, v108
	v_mul_f32_e32 v104, 0xbfb8aa3b, v20
	v_exp_f32_e32 v106, v104
	v_mul_f32_e32 v104, 0xbfb8aa3b, v21
	v_exp_f32_e32 v107, v104
	v_mul_f32_e32 v108, 0xbfb8aa3b, v23
	v_exp_f32_e32 v110, v108
	v_mul_f32_e32 v111, 0xbfb8aa3b, v17
	v_add_f32_e32 v107, 1.0, v107
	v_rcp_f32_e32 v108, v107
	v_add_f32_e32 v107, 1.0, v109
	v_add_f32_e32 v109, 1.0, v110
	v_mul_f32_e32 v110, 0xbfb8aa3b, v16
	v_exp_f32_e32 v111, v111
	v_mul_f32_e32 v112, 0xbfb8aa3b, v18
	v_exp_f32_e32 v110, v110
	v_exp_f32_e32 v113, v112
	v_mul_f32_e32 v112, 0xbfb8aa3b, v19
	v_exp_f32_e32 v114, v112
	v_add_f32_e32 v106, 1.0, v106
	v_rcp_f32_e32 v106, v106
	v_rcp_f32_e32 v107, v107
	v_add_f32_e32 v111, 1.0, v111
	v_rcp_f32_e32 v109, v109
	v_add_f32_e32 v110, 1.0, v110
	v_rcp_f32_e32 v112, v111
	v_add_f32_e32 v111, 1.0, v113
	v_mad_i64_i32 v[104:105], s[6:7], v97, s60, v[68:69]
	v_rcp_f32_e32 v110, v110
	v_rcp_f32_e32 v111, v111
	v_add_f32_e32 v113, 1.0, v114
	v_rcp_f32_e32 v113, v113
	v_lshl_add_u64 v[114:115], v[104:105], 0, v[152:153]
	v_mov_b32_e32 v104, v28
	v_mov_b32_e32 v105, v30
	v_pk_mul_f32 v[104:105], v[104:105], v[106:107]
	v_mov_b32_e32 v106, v29
	v_mov_b32_e32 v107, v31
	v_pk_mul_f32 v[106:107], v[106:107], v[108:109]
	v_mov_b32_e32 v108, v24
	v_mov_b32_e32 v109, v26
	v_pk_mul_f32 v[108:109], v[108:109], v[110:111]
	v_mov_b32_e32 v110, v25
	v_mov_b32_e32 v111, v27
	v_pk_mul_f32 v[110:111], v[110:111], v[112:113]
	v_bfe_u32 v116, v107, 16, 1
	v_bfe_u32 v112, v111, 16, 1
	v_bfe_u32 v113, v110, 16, 1
	v_bfe_u32 v117, v106, 16, 1
	v_add3_u32 v117, v106, v117, s96
	v_add3_u32 v116, v107, v116, s96
	v_add3_u32 v106, v110, v113, s96
	v_add3_u32 v107, v111, v112, s96
	v_bfe_u32 v110, v104, 16, 1
	v_bfe_u32 v111, v105, 16, 1
	v_bfe_u32 v112, v108, 16, 1
	v_bfe_u32 v113, v109, 16, 1
	v_add3_u32 v109, v109, v113, s96
	v_add3_u32 v108, v108, v112, s96
	v_add3_u32 v105, v105, v111, s96
	v_add3_u32 v104, v104, v110, s96
	v_lshrrev_b32_e32 v104, 16, v104
	v_lshrrev_b32_e32 v105, 16, v105
	v_lshrrev_b32_e32 v108, 16, v108
	v_lshrrev_b32_e32 v109, 16, v109
	v_and_or_b32 v107, v107, s97, v109
	v_and_or_b32 v106, v106, s97, v108
	v_and_or_b32 v105, v116, s97, v105
	v_and_or_b32 v104, v117, s97, v104
	s_waitcnt lgkmcnt(0)
	global_store_dwordx4 v[240:241], v[216:219], off offset:2560
	ds_bpermute_b32 v208, v194, v104
	ds_bpermute_b32 v209, v194, v105
	ds_bpermute_b32 v210, v194, v106
	ds_bpermute_b32 v211, v194, v107
	v_lshl_add_u64 v[198:199], v[114:115], 0, v[196:197]
	v_mul_f32_e32 v109, 0xbfb8aa3b, v1
	v_exp_f32_e32 v109, v109
	v_mul_f32_e32 v105, 0xbfb8aa3b, v5
	v_mul_f32_e32 v106, 0xbfb8aa3b, v6
	v_exp_f32_e32 v105, v105
	v_exp_f32_e32 v107, v106
	v_mul_f32_e32 v106, 0xbfb8aa3b, v7
	v_exp_f32_e32 v108, v106
	v_mul_f32_e32 v104, 0xbfb8aa3b, v4
	v_exp_f32_e32 v104, v104
	v_add_f32_e32 v105, 1.0, v105
	v_rcp_f32_e32 v106, v105
	v_add_f32_e32 v105, 1.0, v107
	v_add_f32_e32 v107, 1.0, v108
	v_mul_f32_e32 v108, 0xbfb8aa3b, v0
	v_mul_f32_e32 v110, 0xbfb8aa3b, v2
	v_exp_f32_e32 v108, v108
	v_exp_f32_e32 v111, v110
	v_mul_f32_e32 v110, 0xbfb8aa3b, v3
	v_exp_f32_e32 v112, v110
	v_add_f32_e32 v104, 1.0, v104
	v_rcp_f32_e32 v104, v104
	v_rcp_f32_e32 v105, v105
	v_add_f32_e32 v109, 1.0, v109
	v_rcp_f32_e32 v107, v107
	v_add_f32_e32 v108, 1.0, v108
	v_rcp_f32_e32 v110, v109
	v_add_f32_e32 v109, 1.0, v111
	v_rcp_f32_e32 v108, v108
	v_rcp_f32_e32 v109, v109
	v_add_f32_e32 v111, 1.0, v112
	v_rcp_f32_e32 v111, v111
	v_mov_b32_e32 v112, v12
	v_mov_b32_e32 v113, v14
	v_pk_mul_f32 v[104:105], v[112:113], v[104:105]
	v_mov_b32_e32 v112, v13
	v_mov_b32_e32 v113, v15
	v_pk_mul_f32 v[106:107], v[112:113], v[106:107]
	v_mov_b32_e32 v112, v8
	v_mov_b32_e32 v113, v10
	v_pk_mul_f32 v[108:109], v[112:113], v[108:109]
	v_mov_b32_e32 v112, v9
	v_mov_b32_e32 v113, v11
	v_pk_mul_f32 v[110:111], v[112:113], v[110:111]
	v_bfe_u32 v114, v107, 16, 1
	v_bfe_u32 v112, v111, 16, 1
	v_bfe_u32 v113, v110, 16, 1
	v_bfe_u32 v115, v106, 16, 1
	v_add3_u32 v115, v106, v115, s96
	v_add3_u32 v114, v107, v114, s96
	v_add3_u32 v106, v110, v113, s96
	v_add3_u32 v107, v111, v112, s96
	v_bfe_u32 v110, v104, 16, 1
	v_bfe_u32 v111, v105, 16, 1
	v_bfe_u32 v112, v108, 16, 1
	v_bfe_u32 v113, v109, 16, 1
	v_add3_u32 v109, v109, v113, s96
	v_add3_u32 v108, v108, v112, s96
	v_add3_u32 v105, v105, v111, s96
	v_add3_u32 v104, v104, v110, s96
	v_mad_i64_i32 v[68:69], s[6:7], v81, s60, v[68:69]
	v_lshrrev_b32_e32 v104, 16, v104
	v_lshrrev_b32_e32 v105, 16, v105
	v_lshrrev_b32_e32 v108, 16, v108
	v_lshrrev_b32_e32 v109, 16, v109
	v_lshl_add_u64 v[68:69], v[68:69], 0, v[152:153]
	v_and_or_b32 v107, v107, s97, v109
	v_and_or_b32 v106, v106, s97, v108
	v_and_or_b32 v105, v114, s97, v105
	v_and_or_b32 v104, v115, s97, v104
	s_waitcnt lgkmcnt(0)
	global_store_dwordx4 v[198:199], v[208:211], off offset:2560
	ds_bpermute_b32 v216, v194, v104
	ds_bpermute_b32 v217, v194, v105
	ds_bpermute_b32 v218, v194, v106
	ds_bpermute_b32 v219, v194, v107
	v_lshl_add_u64 v[240:241], v[68:69], 0, v[196:197]
	s_waitcnt lgkmcnt(0)
	global_store_dwordx4 v[240:241], v[216:219], off offset:2560
	s_mov_b64 s[6:7], 0
.LBB0_201:
	s_andn2_b64 vcc, exec, s[6:7]
	s_cbranch_vccnz .LBB0_203
	v_or_b32_e32 v152, s22, v186
	v_mov_b64_e32 v[68:69], s[70:71]
	v_mad_i64_i32 v[106:107], s[6:7], v172, s60, v[68:69]
	v_lshlrev_b64 v[104:105], 1, v[152:153]
	v_lshl_add_u64 v[110:111], v[106:107], 0, v[104:105]
	v_bfe_u32 v106, v140, 16, 1
	v_add3_u32 v106, v140, v106, s96
	v_bfe_u32 v107, v141, 16, 1
	v_lshrrev_b32_e32 v106, 16, v106
	v_add3_u32 v107, v141, v107, s96
	v_and_or_b32 v106, v107, s97, v106
	v_bfe_u32 v107, v142, 16, 1
	v_add3_u32 v107, v142, v107, s96
	v_bfe_u32 v108, v143, 16, 1
	v_lshrrev_b32_e32 v107, 16, v107
	v_add3_u32 v108, v143, v108, s96
	v_and_or_b32 v107, v108, s97, v107
	v_bfe_u32 v108, v136, 16, 1
	v_add3_u32 v108, v136, v108, s96
	v_bfe_u32 v109, v137, 16, 1
	v_lshrrev_b32_e32 v108, 16, v108
	v_add3_u32 v109, v137, v109, s96
	v_and_or_b32 v108, v109, s97, v108
	v_bfe_u32 v109, v138, 16, 1
	v_add3_u32 v109, v138, v109, s96
	v_bfe_u32 v112, v139, 16, 1
	v_lshrrev_b32_e32 v109, 16, v109
	v_add3_u32 v112, v139, v112, s96
	v_and_or_b32 v109, v112, s97, v109
	ds_bpermute_b32 v208, v194, v106
	ds_bpermute_b32 v209, v194, v107
	ds_bpermute_b32 v210, v194, v108
	ds_bpermute_b32 v211, v194, v109
	v_lshl_add_u64 v[198:199], v[110:111], 0, v[196:197]
	v_bfe_u32 v112, v175, 16, 1
	v_add3_u32 v112, v175, v112, s96
	v_bfe_u32 v106, v180, 16, 1
	v_add3_u32 v106, v180, v106, s96
	v_bfe_u32 v107, v181, 16, 1
	v_lshrrev_b32_e32 v106, 16, v106
	v_add3_u32 v107, v181, v107, s96
	v_and_or_b32 v106, v107, s97, v106
	v_bfe_u32 v107, v178, 16, 1
	v_add3_u32 v107, v178, v107, s96
	v_bfe_u32 v108, v179, 16, 1
	v_lshrrev_b32_e32 v107, 16, v107
	v_add3_u32 v108, v179, v108, s96
	v_and_or_b32 v107, v108, s97, v107
	v_bfe_u32 v108, v176, 16, 1
	v_add3_u32 v108, v176, v108, s96
	v_bfe_u32 v109, v177, 16, 1
	v_lshrrev_b32_e32 v108, 16, v108
	v_add3_u32 v109, v177, v109, s96
	v_and_or_b32 v108, v109, s97, v108
	v_bfe_u32 v109, v174, 16, 1
	v_add3_u32 v109, v174, v109, s96
	v_lshrrev_b32_e32 v109, 16, v109
	v_and_or_b32 v109, v112, s97, v109
	s_waitcnt lgkmcnt(0)
	global_store_dwordx4 v[198:199], v[208:211], off
	ds_bpermute_b32 v216, v194, v106
	ds_bpermute_b32 v217, v194, v107
	ds_bpermute_b32 v218, v194, v108
	ds_bpermute_b32 v219, v194, v109
	v_lshl_add_u64 v[240:241], v[110:111], 0, v[196:197]
	v_bfe_u32 v112, v123, 16, 1
	v_add3_u32 v112, v123, v112, s96
	v_mad_i64_i32 v[106:107], s[6:7], v128, s60, v[68:69]
	v_lshl_add_u64 v[110:111], v[106:107], 0, v[104:105]
	v_bfe_u32 v106, v124, 16, 1
	v_add3_u32 v106, v124, v106, s96
	v_bfe_u32 v107, v125, 16, 1
	v_lshrrev_b32_e32 v106, 16, v106
	v_add3_u32 v107, v125, v107, s96
	v_and_or_b32 v106, v107, s97, v106
	v_bfe_u32 v107, v126, 16, 1
	v_add3_u32 v107, v126, v107, s96
	v_bfe_u32 v108, v127, 16, 1
	v_lshrrev_b32_e32 v107, 16, v107
	v_add3_u32 v108, v127, v108, s96
	v_and_or_b32 v107, v108, s97, v107
	v_bfe_u32 v108, v120, 16, 1
	v_add3_u32 v108, v120, v108, s96
	v_bfe_u32 v109, v121, 16, 1
	v_lshrrev_b32_e32 v108, 16, v108
	v_add3_u32 v109, v121, v109, s96
	v_and_or_b32 v108, v109, s97, v108
	v_bfe_u32 v109, v122, 16, 1
	v_add3_u32 v109, v122, v109, s96
	v_lshrrev_b32_e32 v109, 16, v109
	v_and_or_b32 v109, v112, s97, v109
	s_waitcnt lgkmcnt(0)
	global_store_dwordx4 v[240:241], v[216:219], off offset:256
	ds_bpermute_b32 v208, v194, v106
	ds_bpermute_b32 v209, v194, v107
	ds_bpermute_b32 v210, v194, v108
	ds_bpermute_b32 v211, v194, v109
	v_lshl_add_u64 v[198:199], v[110:111], 0, v[196:197]
	v_bfe_u32 v112, v103, 16, 1
	v_add3_u32 v112, v103, v112, s96
	v_bfe_u32 v106, v134, 16, 1
	v_add3_u32 v106, v134, v106, s96
	v_bfe_u32 v107, v135, 16, 1
	v_lshrrev_b32_e32 v106, 16, v106
	v_add3_u32 v107, v135, v107, s96
	v_and_or_b32 v106, v107, s97, v106
	v_bfe_u32 v107, v132, 16, 1
	v_add3_u32 v107, v132, v107, s96
	v_bfe_u32 v108, v133, 16, 1
	v_lshrrev_b32_e32 v107, 16, v107
	v_add3_u32 v108, v133, v108, s96
	v_and_or_b32 v107, v108, s97, v107
	v_bfe_u32 v108, v130, 16, 1
	v_add3_u32 v108, v130, v108, s96
	v_bfe_u32 v109, v131, 16, 1
	v_lshrrev_b32_e32 v108, 16, v108
	v_add3_u32 v109, v131, v109, s96
	v_and_or_b32 v108, v109, s97, v108
	v_bfe_u32 v109, v102, 16, 1
	v_add3_u32 v109, v102, v109, s96
	v_lshrrev_b32_e32 v109, 16, v109
	v_and_or_b32 v109, v112, s97, v109
	s_waitcnt lgkmcnt(0)
	global_store_dwordx4 v[198:199], v[208:211], off
	ds_bpermute_b32 v216, v194, v106
	ds_bpermute_b32 v217, v194, v107
	ds_bpermute_b32 v218, v194, v108
	ds_bpermute_b32 v219, v194, v109
	v_lshl_add_u64 v[240:241], v[110:111], 0, v[196:197]
	v_bfe_u32 v112, v91, 16, 1
	v_add3_u32 v112, v91, v112, s96
	v_mad_i64_i32 v[106:107], s[6:7], v96, s60, v[68:69]
	v_lshl_add_u64 v[110:111], v[106:107], 0, v[104:105]
	v_bfe_u32 v106, v92, 16, 1
	v_add3_u32 v106, v92, v106, s96
	v_bfe_u32 v107, v93, 16, 1
	v_lshrrev_b32_e32 v106, 16, v106
	v_add3_u32 v107, v93, v107, s96
	v_and_or_b32 v106, v107, s97, v106
	v_bfe_u32 v107, v94, 16, 1
	v_add3_u32 v107, v94, v107, s96
	v_bfe_u32 v108, v95, 16, 1
	v_lshrrev_b32_e32 v107, 16, v107
	v_add3_u32 v108, v95, v108, s96
	v_and_or_b32 v107, v108, s97, v107
	v_bfe_u32 v108, v88, 16, 1
	v_add3_u32 v108, v88, v108, s96
	v_bfe_u32 v109, v89, 16, 1
	v_lshrrev_b32_e32 v108, 16, v108
	v_add3_u32 v109, v89, v109, s96
	v_and_or_b32 v108, v109, s97, v108
	v_bfe_u32 v109, v90, 16, 1
	v_add3_u32 v109, v90, v109, s96
	v_lshrrev_b32_e32 v109, 16, v109
	v_and_or_b32 v109, v112, s97, v109
	s_waitcnt lgkmcnt(0)
	global_store_dwordx4 v[240:241], v[216:219], off offset:256
	ds_bpermute_b32 v208, v194, v106
	ds_bpermute_b32 v209, v194, v107
	ds_bpermute_b32 v210, v194, v108
	ds_bpermute_b32 v211, v194, v109
	v_lshl_add_u64 v[198:199], v[110:111], 0, v[196:197]
	v_bfe_u32 v112, v85, 16, 1
	v_add3_u32 v112, v85, v112, s96
	v_bfe_u32 v106, v100, 16, 1
	v_add3_u32 v106, v100, v106, s96
	v_bfe_u32 v107, v101, 16, 1
	v_lshrrev_b32_e32 v106, 16, v106
	v_add3_u32 v107, v101, v107, s96
	v_and_or_b32 v106, v107, s97, v106
	v_bfe_u32 v107, v98, 16, 1
	v_add3_u32 v107, v98, v107, s96
	v_bfe_u32 v108, v99, 16, 1
	v_lshrrev_b32_e32 v107, 16, v107
	v_add3_u32 v108, v99, v108, s96
	v_and_or_b32 v107, v108, s97, v107
	v_bfe_u32 v108, v86, 16, 1
	v_add3_u32 v108, v86, v108, s96
	v_bfe_u32 v109, v87, 16, 1
	v_lshrrev_b32_e32 v108, 16, v108
	v_add3_u32 v109, v87, v109, s96
	v_and_or_b32 v108, v109, s97, v108
	v_bfe_u32 v109, v84, 16, 1
	v_add3_u32 v109, v84, v109, s96
	v_lshrrev_b32_e32 v109, 16, v109
	v_and_or_b32 v109, v112, s97, v109
	s_waitcnt lgkmcnt(0)
	global_store_dwordx4 v[198:199], v[208:211], off
	ds_bpermute_b32 v216, v194, v106
	ds_bpermute_b32 v217, v194, v107
	ds_bpermute_b32 v218, v194, v108
	ds_bpermute_b32 v219, v194, v109
	v_lshl_add_u64 v[240:241], v[110:111], 0, v[196:197]
	v_bfe_u32 v112, v75, 16, 1
	v_add3_u32 v112, v75, v112, s96
	v_mad_i64_i32 v[106:107], s[6:7], v80, s60, v[68:69]
	v_lshl_add_u64 v[110:111], v[106:107], 0, v[104:105]
	v_bfe_u32 v106, v76, 16, 1
	v_add3_u32 v106, v76, v106, s96
	v_bfe_u32 v107, v77, 16, 1
	v_lshrrev_b32_e32 v106, 16, v106
	v_add3_u32 v107, v77, v107, s96
	v_and_or_b32 v106, v107, s97, v106
	v_bfe_u32 v107, v78, 16, 1
	v_add3_u32 v107, v78, v107, s96
	v_bfe_u32 v108, v79, 16, 1
	v_lshrrev_b32_e32 v107, 16, v107
	v_add3_u32 v108, v79, v108, s96
	v_and_or_b32 v107, v108, s97, v107
	v_bfe_u32 v108, v72, 16, 1
	v_add3_u32 v108, v72, v108, s96
	v_bfe_u32 v109, v73, 16, 1
	v_lshrrev_b32_e32 v108, 16, v108
	v_add3_u32 v109, v73, v109, s96
	v_and_or_b32 v108, v109, s97, v108
	v_bfe_u32 v109, v74, 16, 1
	v_add3_u32 v109, v74, v109, s96
	v_lshrrev_b32_e32 v109, 16, v109
	v_and_or_b32 v109, v112, s97, v109
	s_waitcnt lgkmcnt(0)
	global_store_dwordx4 v[240:241], v[216:219], off offset:256
	ds_bpermute_b32 v208, v194, v106
	ds_bpermute_b32 v209, v194, v107
	ds_bpermute_b32 v210, v194, v108
	ds_bpermute_b32 v211, v194, v109
	v_lshl_add_u64 v[198:199], v[110:111], 0, v[196:197]
	v_bfe_u32 v112, v67, 16, 1
	v_add3_u32 v112, v67, v112, s96
	v_bfe_u32 v106, v82, 16, 1
	v_add3_u32 v106, v82, v106, s96
	v_bfe_u32 v107, v83, 16, 1
	v_lshrrev_b32_e32 v106, 16, v106
	v_add3_u32 v107, v83, v107, s96
	v_and_or_b32 v106, v107, s97, v106
	v_bfe_u32 v107, v70, 16, 1
	v_add3_u32 v107, v70, v107, s96
	v_bfe_u32 v108, v71, 16, 1
	v_lshrrev_b32_e32 v107, 16, v107
	v_add3_u32 v108, v71, v108, s96
	v_and_or_b32 v107, v108, s97, v107
	v_bfe_u32 v108, v64, 16, 1
	v_add3_u32 v108, v64, v108, s96
	v_bfe_u32 v109, v65, 16, 1
	v_lshrrev_b32_e32 v108, 16, v108
	v_add3_u32 v109, v65, v109, s96
	v_and_or_b32 v108, v109, s97, v108
	v_bfe_u32 v109, v66, 16, 1
	v_add3_u32 v109, v66, v109, s96
	v_lshrrev_b32_e32 v109, 16, v109
	v_and_or_b32 v109, v112, s97, v109
	s_waitcnt lgkmcnt(0)
	global_store_dwordx4 v[198:199], v[208:211], off
	ds_bpermute_b32 v216, v194, v106
	ds_bpermute_b32 v217, v194, v107
	ds_bpermute_b32 v218, v194, v108
	ds_bpermute_b32 v219, v194, v109
	v_lshl_add_u64 v[240:241], v[110:111], 0, v[196:197]
	v_bfe_u32 v112, v59, 16, 1
	v_add3_u32 v112, v59, v112, s96
	v_mad_i64_i32 v[106:107], s[6:7], v173, s60, v[68:69]
	v_lshl_add_u64 v[110:111], v[106:107], 0, v[104:105]
	v_bfe_u32 v106, v60, 16, 1
	v_add3_u32 v106, v60, v106, s96
	v_bfe_u32 v107, v61, 16, 1
	v_lshrrev_b32_e32 v106, 16, v106
	v_add3_u32 v107, v61, v107, s96
	v_and_or_b32 v106, v107, s97, v106
	v_bfe_u32 v107, v62, 16, 1
	v_add3_u32 v107, v62, v107, s96
	v_bfe_u32 v108, v63, 16, 1
	v_lshrrev_b32_e32 v107, 16, v107
	v_add3_u32 v108, v63, v108, s96
	v_and_or_b32 v107, v108, s97, v107
	v_bfe_u32 v108, v56, 16, 1
	v_add3_u32 v108, v56, v108, s96
	v_bfe_u32 v109, v57, 16, 1
	v_lshrrev_b32_e32 v108, 16, v108
	v_add3_u32 v109, v57, v109, s96
	v_and_or_b32 v108, v109, s97, v108
	v_bfe_u32 v109, v58, 16, 1
	v_add3_u32 v109, v58, v109, s96
	v_lshrrev_b32_e32 v109, 16, v109
	v_and_or_b32 v109, v112, s97, v109
	s_waitcnt lgkmcnt(0)
	global_store_dwordx4 v[240:241], v[216:219], off offset:256
	ds_bpermute_b32 v208, v194, v106
	ds_bpermute_b32 v209, v194, v107
	ds_bpermute_b32 v210, v194, v108
	ds_bpermute_b32 v211, v194, v109
	v_lshl_add_u64 v[198:199], v[110:111], 0, v[196:197]
	v_bfe_u32 v112, v51, 16, 1
	v_add3_u32 v112, v51, v112, s96
	v_bfe_u32 v106, v52, 16, 1
	v_add3_u32 v106, v52, v106, s96
	v_bfe_u32 v107, v53, 16, 1
	v_lshrrev_b32_e32 v106, 16, v106
	v_add3_u32 v107, v53, v107, s96
	v_and_or_b32 v106, v107, s97, v106
	v_bfe_u32 v107, v54, 16, 1
	v_add3_u32 v107, v54, v107, s96
	v_bfe_u32 v108, v55, 16, 1
	v_lshrrev_b32_e32 v107, 16, v107
	v_add3_u32 v108, v55, v108, s96
	v_and_or_b32 v107, v108, s97, v107
	v_bfe_u32 v108, v48, 16, 1
	v_add3_u32 v108, v48, v108, s96
	v_bfe_u32 v109, v49, 16, 1
	v_lshrrev_b32_e32 v108, 16, v108
	v_add3_u32 v109, v49, v109, s96
	v_and_or_b32 v108, v109, s97, v108
	v_bfe_u32 v109, v50, 16, 1
	v_add3_u32 v109, v50, v109, s96
	v_lshrrev_b32_e32 v109, 16, v109
	v_and_or_b32 v109, v112, s97, v109
	s_waitcnt lgkmcnt(0)
	global_store_dwordx4 v[198:199], v[208:211], off
	ds_bpermute_b32 v216, v194, v106
	ds_bpermute_b32 v217, v194, v107
	ds_bpermute_b32 v218, v194, v108
	ds_bpermute_b32 v219, v194, v109
	v_lshl_add_u64 v[240:241], v[110:111], 0, v[196:197]
	v_bfe_u32 v112, v43, 16, 1
	v_add3_u32 v112, v43, v112, s96
	v_mad_i64_i32 v[106:107], s[6:7], v129, s60, v[68:69]
	v_lshl_add_u64 v[110:111], v[106:107], 0, v[104:105]
	v_bfe_u32 v106, v44, 16, 1
	v_add3_u32 v106, v44, v106, s96
	v_bfe_u32 v107, v45, 16, 1
	v_lshrrev_b32_e32 v106, 16, v106
	v_add3_u32 v107, v45, v107, s96
	v_and_or_b32 v106, v107, s97, v106
	v_bfe_u32 v107, v46, 16, 1
	v_add3_u32 v107, v46, v107, s96
	v_bfe_u32 v108, v47, 16, 1
	v_lshrrev_b32_e32 v107, 16, v107
	v_add3_u32 v108, v47, v108, s96
	v_and_or_b32 v107, v108, s97, v107
	v_bfe_u32 v108, v40, 16, 1
	v_add3_u32 v108, v40, v108, s96
	v_bfe_u32 v109, v41, 16, 1
	v_lshrrev_b32_e32 v108, 16, v108
	v_add3_u32 v109, v41, v109, s96
	v_and_or_b32 v108, v109, s97, v108
	v_bfe_u32 v109, v42, 16, 1
	v_add3_u32 v109, v42, v109, s96
	v_lshrrev_b32_e32 v109, 16, v109
	v_and_or_b32 v109, v112, s97, v109
	s_waitcnt lgkmcnt(0)
	global_store_dwordx4 v[240:241], v[216:219], off offset:256
	ds_bpermute_b32 v208, v194, v106
	ds_bpermute_b32 v209, v194, v107
	ds_bpermute_b32 v210, v194, v108
	ds_bpermute_b32 v211, v194, v109
	v_lshl_add_u64 v[198:199], v[110:111], 0, v[196:197]
	v_bfe_u32 v112, v35, 16, 1
	v_add3_u32 v112, v35, v112, s96
	v_bfe_u32 v106, v36, 16, 1
	v_add3_u32 v106, v36, v106, s96
	v_bfe_u32 v107, v37, 16, 1
	v_lshrrev_b32_e32 v106, 16, v106
	v_add3_u32 v107, v37, v107, s96
	v_and_or_b32 v106, v107, s97, v106
	v_bfe_u32 v107, v38, 16, 1
	v_add3_u32 v107, v38, v107, s96
	v_bfe_u32 v108, v39, 16, 1
	v_lshrrev_b32_e32 v107, 16, v107
	v_add3_u32 v108, v39, v108, s96
	v_and_or_b32 v107, v108, s97, v107
	v_bfe_u32 v108, v32, 16, 1
	v_add3_u32 v108, v32, v108, s96
	v_bfe_u32 v109, v33, 16, 1
	v_lshrrev_b32_e32 v108, 16, v108
	v_add3_u32 v109, v33, v109, s96
	v_and_or_b32 v108, v109, s97, v108
	v_bfe_u32 v109, v34, 16, 1
	v_add3_u32 v109, v34, v109, s96
	v_lshrrev_b32_e32 v109, 16, v109
	v_and_or_b32 v109, v112, s97, v109
	s_waitcnt lgkmcnt(0)
	global_store_dwordx4 v[198:199], v[208:211], off
	ds_bpermute_b32 v216, v194, v106
	ds_bpermute_b32 v217, v194, v107
	ds_bpermute_b32 v218, v194, v108
	ds_bpermute_b32 v219, v194, v109
	v_lshl_add_u64 v[240:241], v[110:111], 0, v[196:197]
	v_bfe_u32 v112, v27, 16, 1
	v_add3_u32 v112, v27, v112, s96
	v_mad_i64_i32 v[106:107], s[6:7], v97, s60, v[68:69]
	v_lshl_add_u64 v[110:111], v[106:107], 0, v[104:105]
	v_bfe_u32 v106, v28, 16, 1
	v_add3_u32 v106, v28, v106, s96
	v_bfe_u32 v107, v29, 16, 1
	v_lshrrev_b32_e32 v106, 16, v106
	v_add3_u32 v107, v29, v107, s96
	v_and_or_b32 v106, v107, s97, v106
	v_bfe_u32 v107, v30, 16, 1
	v_add3_u32 v107, v30, v107, s96
	v_bfe_u32 v108, v31, 16, 1
	v_lshrrev_b32_e32 v107, 16, v107
	v_add3_u32 v108, v31, v108, s96
	v_and_or_b32 v107, v108, s97, v107
	v_bfe_u32 v108, v24, 16, 1
	v_add3_u32 v108, v24, v108, s96
	v_bfe_u32 v109, v25, 16, 1
	v_lshrrev_b32_e32 v108, 16, v108
	v_add3_u32 v109, v25, v109, s96
	v_and_or_b32 v108, v109, s97, v108
	v_bfe_u32 v109, v26, 16, 1
	v_add3_u32 v109, v26, v109, s96
	v_lshrrev_b32_e32 v109, 16, v109
	v_and_or_b32 v109, v112, s97, v109
	s_waitcnt lgkmcnt(0)
	global_store_dwordx4 v[240:241], v[216:219], off offset:256
	ds_bpermute_b32 v208, v194, v106
	ds_bpermute_b32 v209, v194, v107
	ds_bpermute_b32 v210, v194, v108
	ds_bpermute_b32 v211, v194, v109
	v_lshl_add_u64 v[198:199], v[110:111], 0, v[196:197]
	v_mad_i64_i32 v[68:69], s[6:7], v81, s60, v[68:69]
	s_nop 0
	v_bfe_u32 v106, v20, 16, 1
	v_add3_u32 v106, v20, v106, s96
	v_bfe_u32 v107, v21, 16, 1
	v_lshrrev_b32_e32 v106, 16, v106
	v_add3_u32 v107, v21, v107, s96
	v_and_or_b32 v106, v107, s97, v106
	v_bfe_u32 v107, v22, 16, 1
	v_add3_u32 v107, v22, v107, s96
	v_bfe_u32 v108, v23, 16, 1
	v_lshrrev_b32_e32 v107, 16, v107
	v_add3_u32 v108, v23, v108, s96
	v_and_or_b32 v107, v108, s97, v107
	v_bfe_u32 v108, v16, 16, 1
	v_add3_u32 v108, v16, v108, s96
	v_bfe_u32 v109, v17, 16, 1
	v_lshrrev_b32_e32 v108, 16, v108
	v_add3_u32 v109, v17, v109, s96
	v_and_or_b32 v108, v109, s97, v108
	v_bfe_u32 v109, v18, 16, 1
	v_lshl_add_u64 v[68:69], v[68:69], 0, v[104:105]
	v_bfe_u32 v104, v12, 16, 1
	v_add3_u32 v109, v18, v109, s96
	v_bfe_u32 v112, v19, 16, 1
	v_add3_u32 v104, v12, v104, s96
	v_bfe_u32 v105, v13, 16, 1
	v_lshrrev_b32_e32 v109, 16, v109
	v_add3_u32 v112, v19, v112, s96
	v_lshrrev_b32_e32 v104, 16, v104
	v_add3_u32 v105, v13, v105, s96
	v_and_or_b32 v109, v112, s97, v109
	v_and_or_b32 v104, v105, s97, v104
	v_bfe_u32 v105, v14, 16, 1
	s_waitcnt lgkmcnt(0)
	global_store_dwordx4 v[198:199], v[208:211], off
	ds_bpermute_b32 v216, v194, v106
	ds_bpermute_b32 v217, v194, v107
	ds_bpermute_b32 v218, v194, v108
	ds_bpermute_b32 v219, v194, v109
	v_lshl_add_u64 v[240:241], v[110:111], 0, v[196:197]
	v_add3_u32 v105, v14, v105, s96
	v_lshrrev_b32_e32 v105, 16, v105
	v_bfe_u32 v106, v15, 16, 1
	v_add3_u32 v106, v15, v106, s96
	v_and_or_b32 v105, v106, s97, v105
	v_bfe_u32 v106, v8, 16, 1
	v_add3_u32 v106, v8, v106, s96
	v_bfe_u32 v107, v9, 16, 1
	v_lshrrev_b32_e32 v106, 16, v106
	v_add3_u32 v107, v9, v107, s96
	v_and_or_b32 v106, v107, s97, v106
	v_bfe_u32 v107, v10, 16, 1
	v_add3_u32 v107, v10, v107, s96
	v_bfe_u32 v108, v11, 16, 1
	v_lshrrev_b32_e32 v107, 16, v107
	v_add3_u32 v108, v11, v108, s96
	v_and_or_b32 v107, v108, s97, v107
	s_waitcnt lgkmcnt(0)
	global_store_dwordx4 v[240:241], v[216:219], off offset:256
	ds_bpermute_b32 v208, v194, v104
	ds_bpermute_b32 v209, v194, v105
	ds_bpermute_b32 v210, v194, v106
	ds_bpermute_b32 v211, v194, v107
	v_lshl_add_u64 v[198:199], v[68:69], 0, v[196:197]
	v_bfe_u32 v108, v3, 16, 1
	v_add3_u32 v108, v3, v108, s96
	v_bfe_u32 v104, v4, 16, 1
	v_add3_u32 v104, v4, v104, s96
	v_bfe_u32 v105, v5, 16, 1
	v_lshrrev_b32_e32 v104, 16, v104
	v_add3_u32 v105, v5, v105, s96
	v_and_or_b32 v104, v105, s97, v104
	v_bfe_u32 v105, v6, 16, 1
	v_add3_u32 v105, v6, v105, s96
	v_bfe_u32 v106, v7, 16, 1
	v_lshrrev_b32_e32 v105, 16, v105
	v_add3_u32 v106, v7, v106, s96
	v_and_or_b32 v105, v106, s97, v105
	v_bfe_u32 v106, v0, 16, 1
	v_add3_u32 v106, v0, v106, s96
	v_bfe_u32 v107, v1, 16, 1
	v_lshrrev_b32_e32 v106, 16, v106
	v_add3_u32 v107, v1, v107, s96
	v_and_or_b32 v106, v107, s97, v106
	v_bfe_u32 v107, v2, 16, 1
	v_add3_u32 v107, v2, v107, s96
	v_lshrrev_b32_e32 v107, 16, v107
	v_and_or_b32 v107, v108, s97, v107
	s_waitcnt lgkmcnt(0)
	global_store_dwordx4 v[198:199], v[208:211], off
	ds_bpermute_b32 v216, v194, v104
	ds_bpermute_b32 v217, v194, v105
	ds_bpermute_b32 v218, v194, v106
	ds_bpermute_b32 v219, v194, v107
	v_lshl_add_u64 v[240:241], v[68:69], 0, v[196:197]
	s_waitcnt lgkmcnt(0)
	global_store_dwordx4 v[240:241], v[216:219], off offset:256

.LBB0_473:
	s_add_u32 s6, s4, 0xfffc0080
	s_addc_u32 s7, s5, -1
	s_add_i32 s51, 0, 0x10000
	s_cmp_eq_u32 s50, 12
	s_cselect_b32 s9, s15, s7
	s_cselect_b32 s8, s23, s6
	v_add_u32_e32 v152, s51, v147
	s_cselect_b32 s7, s17, s47
	s_cselect_b32 s6, s41, s46
	s_add_i32 s53, 0, 0x14000
	ds_read_b128 v[140:143], v152
	ds_read_b128 v[170:173], v152 offset:1024
	ds_read_b128 v[174:177], v152 offset:2048
	ds_read_b128 v[178:181], v152 offset:3072
	v_add_u32_e32 v152, s53, v147
	ds_read_b128 v[182:185], v152
	ds_read_b128 v[186:189], v152 offset:1024
	ds_read_b128 v[190:193], v152 offset:2048
	ds_read_b128 v[194:197], v152 offset:3072
	v_lshl_add_u64 v[154:155], s[4:5], 0, v[136:137]
	s_add_i32 m0, s25, 0xc000
	ds_read_b128 v[198:201], v167
	ds_read_b128 v[202:205], v167 offset:1024
	ds_read_b128 v[206:209], v167 offset:2048
	ds_read_b128 v[210:213], v167 offset:3072
	ds_read_b128 v[214:217], v167 offset:4096
	ds_read_b128 v[218:221], v167 offset:5120
	ds_read_b128 v[222:225], v167 offset:6144
	ds_read_b128 v[240:243], v167 offset:7168
	global_load_lds_dwordx4 v[154:155], off
	v_lshl_add_u64 v[154:155], s[4:5], 0, v[138:139]
	s_add_i32 m0, s25, 0xe000
	s_nop 0
	global_load_lds_dwordx4 v[154:155], off
	s_waitcnt vmcnt(8)
	s_waitcnt lgkmcnt(0)
	s_barrier
	s_setprio 1
	s_waitcnt lgkmcnt(0)
	v_mfma_f32_16x16x32_bf16 v[116:119], v[140:143], v[198:201], v[116:119]
	v_mfma_f32_16x16x32_bf16 v[112:115], v[174:177], v[198:201], v[112:115]
	v_mfma_f32_16x16x32_bf16 v[100:103], v[140:143], v[206:209], v[100:103]
	v_mfma_f32_16x16x32_bf16 v[96:99], v[174:177], v[206:209], v[96:99]
	v_mfma_f32_16x16x32_bf16 v[84:87], v[140:143], v[214:217], v[84:87]
	v_mfma_f32_16x16x32_bf16 v[80:83], v[174:177], v[214:217], v[80:83]
	v_mfma_f32_16x16x32_bf16 v[68:71], v[140:143], v[222:225], v[68:71]
	v_mfma_f32_16x16x32_bf16 v[64:67], v[174:177], v[222:225], v[64:67]
	v_mfma_f32_16x16x32_bf16 v[116:119], v[170:173], v[202:205], v[116:119]
	v_mfma_f32_16x16x32_bf16 v[112:115], v[178:181], v[202:205], v[112:115]
	v_mfma_f32_16x16x32_bf16 v[100:103], v[170:173], v[210:213], v[100:103]
	v_mfma_f32_16x16x32_bf16 v[96:99], v[178:181], v[210:213], v[96:99]
	v_mfma_f32_16x16x32_bf16 v[84:87], v[170:173], v[218:221], v[84:87]
	v_mfma_f32_16x16x32_bf16 v[80:83], v[178:181], v[218:221], v[80:83]
	v_mfma_f32_16x16x32_bf16 v[68:71], v[170:173], v[240:243], v[68:71]
	v_mfma_f32_16x16x32_bf16 v[64:67], v[178:181], v[240:243], v[64:67]
	s_setprio 0
	s_setprio 1
	v_mfma_f32_16x16x32_bf16 v[124:127], v[182:185], v[198:201], v[124:127]
	v_mfma_f32_16x16x32_bf16 v[120:123], v[190:193], v[198:201], v[120:123]
	v_mfma_f32_16x16x32_bf16 v[108:111], v[182:185], v[206:209], v[108:111]
	v_mfma_f32_16x16x32_bf16 v[104:107], v[190:193], v[206:209], v[104:107]
	v_mfma_f32_16x16x32_bf16 v[92:95], v[182:185], v[214:217], v[92:95]
	v_mfma_f32_16x16x32_bf16 v[88:91], v[190:193], v[214:217], v[88:91]
	v_mfma_f32_16x16x32_bf16 v[76:79], v[182:185], v[222:225], v[76:79]
	v_mfma_f32_16x16x32_bf16 v[72:75], v[190:193], v[222:225], v[72:75]
	v_mfma_f32_16x16x32_bf16 v[124:127], v[186:189], v[202:205], v[124:127]
	v_mfma_f32_16x16x32_bf16 v[120:123], v[194:197], v[202:205], v[120:123]
	v_mfma_f32_16x16x32_bf16 v[108:111], v[186:189], v[210:213], v[108:111]
	v_mfma_f32_16x16x32_bf16 v[104:107], v[194:197], v[210:213], v[104:107]
	v_mfma_f32_16x16x32_bf16 v[92:95], v[186:189], v[218:221], v[92:95]
	v_mfma_f32_16x16x32_bf16 v[88:91], v[194:197], v[218:221], v[88:91]
	v_mfma_f32_16x16x32_bf16 v[76:79], v[186:189], v[240:243], v[76:79]
	v_mfma_f32_16x16x32_bf16 v[72:75], v[194:197], v[240:243], v[72:75]
	s_setprio 0
	s_barrier
	s_add_i32 s51, s51, s24
	v_lshl_add_u64 v[154:155], s[6:7], 0, v[130:131]
	s_mov_b32 m0, s51
	ds_read_b128 v[198:201], v167 offset:16384
	ds_read_b128 v[202:205], v167 offset:17408
	ds_read_b128 v[206:209], v167 offset:18432
	ds_read_b128 v[210:213], v167 offset:19456
	ds_read_b128 v[214:217], v167 offset:20480
	ds_read_b128 v[218:221], v167 offset:21504
	ds_read_b128 v[222:225], v167 offset:22528
	ds_read_b128 v[240:243], v167 offset:23552
	global_load_lds_dwordx4 v[154:155], off
	s_add_i32 m0, s51, 0x2000
	s_add_u32 s54, s6, 0x40000
	v_lshl_add_u64 v[156:157], s[6:7], 0, v[134:135]
	s_addc_u32 s55, s7, 0
	s_add_i32 s51, s53, s24
	global_load_lds_dwordx4 v[156:157], off
	v_lshl_add_u64 v[158:159], s[54:55], 0, v[130:131]
	s_mov_b32 m0, s51
	v_lshl_add_u64 v[160:161], s[8:9], 0, v[132:133]
	global_load_lds_dwordx4 v[158:159], off
	v_lshl_add_u64 v[158:159], s[54:55], 0, v[134:135]
	s_add_i32 m0, s51, 0x2000
	s_nop 0
	global_load_lds_dwordx4 v[158:159], off
	v_lshl_add_u64 v[158:159], s[8:9], 0, v[128:129]
	s_mov_b32 m0, s25
	s_nop 0
	global_load_lds_dwordx4 v[158:159], off
	s_mov_b32 m0, s28
	s_nop 0
	global_load_lds_dwordx4 v[160:161], off
	s_waitcnt vmcnt(8)
	s_waitcnt lgkmcnt(0)
	s_barrier
	s_setprio 1
	s_waitcnt lgkmcnt(0)
	v_mfma_f32_16x16x32_bf16 v[52:55], v[140:143], v[198:201], v[52:55]
	v_mfma_f32_16x16x32_bf16 v[48:51], v[174:177], v[198:201], v[48:51]
	v_mfma_f32_16x16x32_bf16 v[36:39], v[140:143], v[206:209], v[36:39]
	v_mfma_f32_16x16x32_bf16 v[32:35], v[174:177], v[206:209], v[32:35]
	v_mfma_f32_16x16x32_bf16 v[20:23], v[140:143], v[214:217], v[20:23]
	v_mfma_f32_16x16x32_bf16 v[16:19], v[174:177], v[214:217], v[16:19]
	v_mfma_f32_16x16x32_bf16 v[8:11], v[140:143], v[222:225], v[8:11]
	v_mfma_f32_16x16x32_bf16 v[0:3], v[174:177], v[222:225], v[0:3]
	v_mfma_f32_16x16x32_bf16 v[52:55], v[170:173], v[202:205], v[52:55]
	v_mfma_f32_16x16x32_bf16 v[48:51], v[178:181], v[202:205], v[48:51]
	v_mfma_f32_16x16x32_bf16 v[36:39], v[170:173], v[210:213], v[36:39]
	v_mfma_f32_16x16x32_bf16 v[32:35], v[178:181], v[210:213], v[32:35]
	v_mfma_f32_16x16x32_bf16 v[20:23], v[170:173], v[218:221], v[20:23]
	v_mfma_f32_16x16x32_bf16 v[16:19], v[178:181], v[218:221], v[16:19]
	v_mfma_f32_16x16x32_bf16 v[8:11], v[170:173], v[240:243], v[8:11]
	v_mfma_f32_16x16x32_bf16 v[0:3], v[178:181], v[240:243], v[0:3]
	s_setprio 0
	s_setprio 1
	v_mfma_f32_16x16x32_bf16 v[60:63], v[182:185], v[198:201], v[60:63]
	v_mfma_f32_16x16x32_bf16 v[56:59], v[190:193], v[198:201], v[56:59]
	v_mfma_f32_16x16x32_bf16 v[44:47], v[182:185], v[206:209], v[44:47]
	v_mfma_f32_16x16x32_bf16 v[40:43], v[190:193], v[206:209], v[40:43]
	v_mfma_f32_16x16x32_bf16 v[28:31], v[182:185], v[214:217], v[28:31]
	v_mfma_f32_16x16x32_bf16 v[24:27], v[190:193], v[214:217], v[24:27]
	v_mfma_f32_16x16x32_bf16 v[12:15], v[182:185], v[222:225], v[12:15]
	v_mfma_f32_16x16x32_bf16 v[4:7], v[190:193], v[222:225], v[4:7]
	v_mfma_f32_16x16x32_bf16 v[60:63], v[186:189], v[202:205], v[60:63]
	v_mfma_f32_16x16x32_bf16 v[56:59], v[194:197], v[202:205], v[56:59]
	v_mfma_f32_16x16x32_bf16 v[44:47], v[186:189], v[210:213], v[44:47]
	v_mfma_f32_16x16x32_bf16 v[40:43], v[194:197], v[210:213], v[40:43]
	v_mfma_f32_16x16x32_bf16 v[28:31], v[186:189], v[218:221], v[28:31]
	v_mfma_f32_16x16x32_bf16 v[24:27], v[194:197], v[218:221], v[24:27]
	v_mfma_f32_16x16x32_bf16 v[12:15], v[186:189], v[240:243], v[12:15]
	v_mfma_f32_16x16x32_bf16 v[4:7], v[194:197], v[240:243], v[4:7]
	s_setprio 0
	s_barrier
	s_add_i32 s51, 0, 0x18000
	v_add_u32_e32 v152, s51, v147
	s_add_i32 s53, 0, 0x1c000
	ds_read_b128 v[140:143], v152
	ds_read_b128 v[170:173], v152 offset:1024
	ds_read_b128 v[174:177], v152 offset:2048
	ds_read_b128 v[178:181], v152 offset:3072
	v_add_u32_e32 v152, s53, v147
	ds_read_b128 v[182:185], v152
	ds_read_b128 v[186:189], v152 offset:1024
	ds_read_b128 v[190:193], v152 offset:2048
	ds_read_b128 v[194:197], v152 offset:3072
	s_add_u32 s8, s8, 0x40000
	s_addc_u32 s9, s9, 0
	s_mov_b32 m0, s29
	v_lshl_add_u64 v[226:227], s[8:9], 0, v[128:129]
	ds_read_b128 v[198:201], v167 offset:32768
	ds_read_b128 v[202:205], v167 offset:33792
	ds_read_b128 v[206:209], v167 offset:34816
	ds_read_b128 v[210:213], v167 offset:35840
	ds_read_b128 v[214:217], v167 offset:36864
	ds_read_b128 v[218:221], v167 offset:37888
	ds_read_b128 v[222:225], v167 offset:38912
	ds_read_b128 v[240:243], v167 offset:39936
	global_load_lds_dwordx4 v[226:227], off
	v_lshl_add_u64 v[226:227], s[8:9], 0, v[132:133]
	s_mov_b32 m0, s37
	s_nop 0
	global_load_lds_dwordx4 v[226:227], off
	s_waitcnt vmcnt(8)
	s_waitcnt lgkmcnt(0)
	s_barrier
	s_setprio 1
	s_waitcnt lgkmcnt(0)
	v_mfma_f32_16x16x32_bf16 v[116:119], v[140:143], v[198:201], v[116:119]
	v_mfma_f32_16x16x32_bf16 v[112:115], v[174:177], v[198:201], v[112:115]
	v_mfma_f32_16x16x32_bf16 v[100:103], v[140:143], v[206:209], v[100:103]
	v_mfma_f32_16x16x32_bf16 v[96:99], v[174:177], v[206:209], v[96:99]
	v_mfma_f32_16x16x32_bf16 v[84:87], v[140:143], v[214:217], v[84:87]
	v_mfma_f32_16x16x32_bf16 v[80:83], v[174:177], v[214:217], v[80:83]
	v_mfma_f32_16x16x32_bf16 v[68:71], v[140:143], v[222:225], v[68:71]
	v_mfma_f32_16x16x32_bf16 v[64:67], v[174:177], v[222:225], v[64:67]
	v_mfma_f32_16x16x32_bf16 v[116:119], v[170:173], v[202:205], v[116:119]
	v_mfma_f32_16x16x32_bf16 v[112:115], v[178:181], v[202:205], v[112:115]
	v_mfma_f32_16x16x32_bf16 v[100:103], v[170:173], v[210:213], v[100:103]
	v_mfma_f32_16x16x32_bf16 v[96:99], v[178:181], v[210:213], v[96:99]
	v_mfma_f32_16x16x32_bf16 v[84:87], v[170:173], v[218:221], v[84:87]
	v_mfma_f32_16x16x32_bf16 v[80:83], v[178:181], v[218:221], v[80:83]
	v_mfma_f32_16x16x32_bf16 v[68:71], v[170:173], v[240:243], v[68:71]
	v_mfma_f32_16x16x32_bf16 v[64:67], v[178:181], v[240:243], v[64:67]
	s_setprio 0
	s_setprio 1
	v_mfma_f32_16x16x32_bf16 v[124:127], v[182:185], v[198:201], v[124:127]
	v_mfma_f32_16x16x32_bf16 v[120:123], v[190:193], v[198:201], v[120:123]
	v_mfma_f32_16x16x32_bf16 v[108:111], v[182:185], v[206:209], v[108:111]
	v_mfma_f32_16x16x32_bf16 v[104:107], v[190:193], v[206:209], v[104:107]
	v_mfma_f32_16x16x32_bf16 v[92:95], v[182:185], v[214:217], v[92:95]
	v_mfma_f32_16x16x32_bf16 v[88:91], v[190:193], v[214:217], v[88:91]
	v_mfma_f32_16x16x32_bf16 v[76:79], v[182:185], v[222:225], v[76:79]
	v_mfma_f32_16x16x32_bf16 v[72:75], v[190:193], v[222:225], v[72:75]
	v_mfma_f32_16x16x32_bf16 v[124:127], v[186:189], v[202:205], v[124:127]
	v_mfma_f32_16x16x32_bf16 v[120:123], v[194:197], v[202:205], v[120:123]
	v_mfma_f32_16x16x32_bf16 v[108:111], v[186:189], v[210:213], v[108:111]
	v_mfma_f32_16x16x32_bf16 v[104:107], v[194:197], v[210:213], v[104:107]
	v_mfma_f32_16x16x32_bf16 v[92:95], v[186:189], v[218:221], v[92:95]
	v_mfma_f32_16x16x32_bf16 v[88:91], v[194:197], v[218:221], v[88:91]
	v_mfma_f32_16x16x32_bf16 v[76:79], v[186:189], v[240:243], v[76:79]
	v_mfma_f32_16x16x32_bf16 v[72:75], v[194:197], v[240:243], v[72:75]
	s_setprio 0
	s_barrier
	s_add_i32 s8, s51, s24
	v_lshl_add_u64 v[154:155], v[154:155], 0, s[44:45]
	s_mov_b32 m0, s8
	ds_read_b128 v[198:201], v167 offset:49152
	ds_read_b128 v[202:205], v167 offset:50176
	ds_read_b128 v[206:209], v167 offset:51200
	ds_read_b128 v[210:213], v167 offset:52224
	ds_read_b128 v[214:217], v167 offset:53248
	ds_read_b128 v[218:221], v167 offset:54272
	ds_read_b128 v[222:225], v167 offset:55296
	ds_read_b128 v[240:243], v167 offset:56320
	global_load_lds_dwordx4 v[154:155], off
	s_add_i32 m0, s8, 0x2000
	s_add_u32 s6, s6, 0x40080
	v_lshl_add_u64 v[154:155], v[156:157], 0, s[44:45]
	s_addc_u32 s7, s7, 0
	s_add_i32 s8, s53, s24
	global_load_lds_dwordx4 v[154:155], off
	v_lshl_add_u64 v[154:155], s[6:7], 0, v[130:131]
	s_mov_b32 m0, s8
	s_nop 0
	global_load_lds_dwordx4 v[154:155], off
	v_lshl_add_u64 v[154:155], s[6:7], 0, v[134:135]
	s_add_i32 m0, s8, 0x2000
	s_nop 0
	global_load_lds_dwordx4 v[154:155], off
	v_lshl_add_u64 v[154:155], v[158:159], 0, s[44:45]
	s_mov_b32 m0, s39
	s_nop 0
	global_load_lds_dwordx4 v[154:155], off
	v_lshl_add_u64 v[154:155], v[160:161], 0, s[44:45]
	s_mov_b32 m0, s40
	s_nop 0
	global_load_lds_dwordx4 v[154:155], off
	s_waitcnt vmcnt(8)
	s_waitcnt lgkmcnt(0)
	s_barrier
	s_setprio 1
	s_waitcnt lgkmcnt(0)
	v_mfma_f32_16x16x32_bf16 v[52:55], v[140:143], v[198:201], v[52:55]
	v_mfma_f32_16x16x32_bf16 v[48:51], v[174:177], v[198:201], v[48:51]
	v_mfma_f32_16x16x32_bf16 v[36:39], v[140:143], v[206:209], v[36:39]
	v_mfma_f32_16x16x32_bf16 v[32:35], v[174:177], v[206:209], v[32:35]
	v_mfma_f32_16x16x32_bf16 v[20:23], v[140:143], v[214:217], v[20:23]
	v_mfma_f32_16x16x32_bf16 v[16:19], v[174:177], v[214:217], v[16:19]
	v_mfma_f32_16x16x32_bf16 v[8:11], v[140:143], v[222:225], v[8:11]
	v_mfma_f32_16x16x32_bf16 v[0:3], v[174:177], v[222:225], v[0:3]
	v_mfma_f32_16x16x32_bf16 v[52:55], v[170:173], v[202:205], v[52:55]
	v_mfma_f32_16x16x32_bf16 v[48:51], v[178:181], v[202:205], v[48:51]
	v_mfma_f32_16x16x32_bf16 v[36:39], v[170:173], v[210:213], v[36:39]
	v_mfma_f32_16x16x32_bf16 v[32:35], v[178:181], v[210:213], v[32:35]
	v_mfma_f32_16x16x32_bf16 v[20:23], v[170:173], v[218:221], v[20:23]
	v_mfma_f32_16x16x32_bf16 v[16:19], v[178:181], v[218:221], v[16:19]
	v_mfma_f32_16x16x32_bf16 v[8:11], v[170:173], v[240:243], v[8:11]
	v_mfma_f32_16x16x32_bf16 v[0:3], v[178:181], v[240:243], v[0:3]
	s_setprio 0
	s_setprio 1
	v_mfma_f32_16x16x32_bf16 v[60:63], v[182:185], v[198:201], v[60:63]
	v_mfma_f32_16x16x32_bf16 v[56:59], v[190:193], v[198:201], v[56:59]
	v_mfma_f32_16x16x32_bf16 v[44:47], v[182:185], v[206:209], v[44:47]
	v_mfma_f32_16x16x32_bf16 v[40:43], v[190:193], v[206:209], v[40:43]
	v_mfma_f32_16x16x32_bf16 v[28:31], v[182:185], v[214:217], v[28:31]
	v_mfma_f32_16x16x32_bf16 v[24:27], v[190:193], v[214:217], v[24:27]
	v_mfma_f32_16x16x32_bf16 v[12:15], v[182:185], v[222:225], v[12:15]
	v_mfma_f32_16x16x32_bf16 v[4:7], v[190:193], v[222:225], v[4:7]
	v_mfma_f32_16x16x32_bf16 v[60:63], v[186:189], v[202:205], v[60:63]
	v_mfma_f32_16x16x32_bf16 v[56:59], v[194:197], v[202:205], v[56:59]
	v_mfma_f32_16x16x32_bf16 v[44:47], v[186:189], v[210:213], v[44:47]
	v_mfma_f32_16x16x32_bf16 v[40:43], v[194:197], v[210:213], v[40:43]
	v_mfma_f32_16x16x32_bf16 v[28:31], v[186:189], v[218:221], v[28:31]
	v_mfma_f32_16x16x32_bf16 v[24:27], v[194:197], v[218:221], v[24:27]
	v_mfma_f32_16x16x32_bf16 v[12:15], v[186:189], v[240:243], v[12:15]
	v_mfma_f32_16x16x32_bf16 v[4:7], v[194:197], v[240:243], v[4:7]
	s_setprio 0
	s_barrier
	s_add_i32 s50, s50, 2
	s_add_u32 s4, s4, 0x100
	s_addc_u32 s5, s5, 0
	s_add_u32 s46, s46, 0x100
	s_addc_u32 s47, s47, 0
	s_cmp_gt_u32 s50, 13
	s_cbranch_scc0 .LBB0_473
	v_mbcnt_lo_u32_b32 v194, -1, 0
	v_mbcnt_hi_u32_b32 v194, -1, v194
	v_and_b32_e32 v198, 15, v194
	v_lshrrev_b32_e32 v199, 2, v194
	v_sub_u32_e32 v196, v199, v198
	v_mul_i32_i24_e32 v196, 0x1800, v196
	v_and_b32_e32 v198, 3, v194
	v_lshrrev_b32_e32 v197, 4, v194
	v_sub_u32_e32 v197, v198, v197
	v_lshl_add_u32 v196, v197, 4, v196
	v_ashrrev_i32_e32 v197, 31, v196
	v_lshl_add_u32 v194, v198, 4, v199
	v_lshlrev_b32_e32 v194, 2, v194
	s_and_b64 vcc, exec, s[12:13]
	s_cbranch_vccnz .LBB0_478
	v_lshl_add_u32 v169, s22, 8, v145
	s_cmp_gt_i32 s35, 7
	s_mov_b64 s[4:5], -1
	s_cbranch_scc1 .LBB0_479

.LBB0_479:
	v_mov_b64_e32 v[140:141], s[70:71]
	v_mad_i64_i32 v[140:141], s[4:5], v169, s60, v[140:141]
	s_cmp_gt_u32 s35, 9
	s_mov_b64 s[4:5], -1
	s_cbranch_scc0 .LBB0_481
	v_mul_f32_e32 v143, 0xbfb8aa3b, v125
	v_exp_f32_e32 v143, v143
	v_mul_f32_e32 v152, 0xbfb8aa3b, v126
	v_mul_f32_e32 v154, 0xbfb8aa3b, v127
	v_exp_f32_e32 v152, v152
	v_exp_f32_e32 v155, v154
	v_add_f32_e32 v143, 1.0, v143
	v_rcp_f32_e32 v154, v143
	v_add_f32_e32 v143, 1.0, v152
	v_add_f32_e32 v152, 1.0, v155
	v_mul_f32_e32 v155, 0xbfb8aa3b, v120
	v_exp_f32_e32 v156, v155
	v_mul_f32_e32 v155, 0xbfb8aa3b, v121
	v_exp_f32_e32 v157, v155
	v_mul_f32_e32 v142, 0xbfb8aa3b, v124
	v_exp_f32_e32 v142, v142
	v_rcp_f32_e32 v155, v152
	v_add_f32_e32 v152, 1.0, v156
	v_rcp_f32_e32 v156, v152
	v_add_f32_e32 v152, 1.0, v157
	v_mul_f32_e32 v157, 0xbfb8aa3b, v122
	v_exp_f32_e32 v157, v157
	v_mul_f32_e32 v158, 0xbfb8aa3b, v123
	v_exp_f32_e32 v159, v158
	v_add_f32_e32 v142, 1.0, v142
	v_rcp_f32_e32 v142, v142
	v_rcp_f32_e32 v143, v143
	v_rcp_f32_e32 v158, v152
	v_add_f32_e32 v152, 1.0, v157
	v_rcp_f32_e32 v157, v152
	v_add_f32_e32 v152, 1.0, v159
	v_rcp_f32_e32 v159, v152
	v_mov_b32_e32 v170, v116
	v_mov_b32_e32 v171, v118
	v_pk_mul_f32 v[142:143], v[170:171], v[142:143]
	v_mov_b32_e32 v170, v117
	v_mov_b32_e32 v171, v119
	v_pk_mul_f32 v[154:155], v[170:171], v[154:155]
	v_mov_b32_e32 v170, v112
	v_mov_b32_e32 v171, v114
	v_pk_mul_f32 v[156:157], v[170:171], v[156:157]
	v_mov_b32_e32 v170, v113
	v_mov_b32_e32 v171, v115
	v_pk_mul_f32 v[158:159], v[170:171], v[158:159]
	v_bfe_u32 v172, v155, 16, 1
	v_bfe_u32 v171, v158, 16, 1
	v_add3_u32 v158, v158, v171, s96
	v_bfe_u32 v171, v143, 16, 1
	v_bfe_u32 v170, v159, 16, 1
	v_bfe_u32 v173, v154, 16, 1
	v_add3_u32 v155, v155, v172, s96
	v_bfe_u32 v172, v156, 16, 1
	v_add3_u32 v143, v143, v171, s96
	v_add3_u32 v154, v154, v173, s96
	v_add3_u32 v159, v159, v170, s96
	v_bfe_u32 v170, v142, 16, 1
	v_bfe_u32 v173, v157, 16, 1
	v_add3_u32 v156, v156, v172, s96
	v_lshrrev_b32_e32 v143, 16, v143
	v_add3_u32 v157, v157, v173, s96
	v_add3_u32 v142, v142, v170, s96
	v_lshrrev_b32_e32 v156, 16, v156
	v_and_or_b32 v171, v155, s97, v143
	v_mul_f32_e32 v155, 0xbfb8aa3b, v108
	v_lshl_or_b32 v152, s35, 8, v168
	v_lshrrev_b32_e32 v142, 16, v142
	v_lshrrev_b32_e32 v157, 16, v157
	v_and_or_b32 v172, v158, s97, v156
	v_exp_f32_e32 v156, v155
	v_mul_f32_e32 v155, 0xbfb8aa3b, v109
	v_mul_f32_e32 v158, 0xbfb8aa3b, v110
	v_lshl_add_u64 v[160:161], v[140:141], 0, v[152:153]
	v_and_or_b32 v173, v159, s97, v157
	v_and_or_b32 v170, v154, s97, v142
	v_exp_f32_e32 v157, v155
	v_exp_f32_e32 v159, v158
	v_mul_f32_e32 v158, 0xbfb8aa3b, v111
	ds_bpermute_b32 v208, v194, v170
	ds_bpermute_b32 v209, v194, v171
	ds_bpermute_b32 v210, v194, v172
	ds_bpermute_b32 v211, v194, v173
	v_lshl_add_u64 v[198:199], v[160:161], 0, v[196:197]
	v_exp_f32_e32 v160, v158
	v_add_f32_e32 v157, 1.0, v157
	v_mul_f32_e32 v161, 0xbfb8aa3b, v105
	v_rcp_f32_e32 v158, v157
	v_add_f32_e32 v157, 1.0, v159
	v_add_f32_e32 v159, 1.0, v160
	v_mul_f32_e32 v160, 0xbfb8aa3b, v104
	v_exp_f32_e32 v161, v161
	v_mul_f32_e32 v170, 0xbfb8aa3b, v106
	v_exp_f32_e32 v160, v160
	v_exp_f32_e32 v171, v170
	v_mul_f32_e32 v170, 0xbfb8aa3b, v107
	v_exp_f32_e32 v172, v170
	v_add_f32_e32 v156, 1.0, v156
	v_rcp_f32_e32 v156, v156
	v_rcp_f32_e32 v157, v157
	v_add_f32_e32 v161, 1.0, v161
	v_rcp_f32_e32 v159, v159
	v_add_f32_e32 v160, 1.0, v160
	v_rcp_f32_e32 v170, v161
	v_add_f32_e32 v161, 1.0, v171
	v_rcp_f32_e32 v160, v160
	v_rcp_f32_e32 v161, v161
	v_add_f32_e32 v171, 1.0, v172
	v_rcp_f32_e32 v171, v171
	v_mov_b32_e32 v172, v100
	v_mov_b32_e32 v173, v102
	v_pk_mul_f32 v[156:157], v[172:173], v[156:157]
	v_mov_b32_e32 v172, v101
	v_mov_b32_e32 v173, v103
	v_pk_mul_f32 v[158:159], v[172:173], v[158:159]
	v_mov_b32_e32 v172, v96
	v_mov_b32_e32 v173, v98
	v_pk_mul_f32 v[160:161], v[172:173], v[160:161]
	v_mov_b32_e32 v172, v97
	v_mov_b32_e32 v173, v99
	v_pk_mul_f32 v[170:171], v[172:173], v[170:171]
	v_bfe_u32 v174, v159, 16, 1
	v_bfe_u32 v172, v171, 16, 1
	v_bfe_u32 v173, v170, 16, 1
	v_bfe_u32 v175, v158, 16, 1
	v_add3_u32 v158, v158, v175, s96
	v_add3_u32 v159, v159, v174, s96
	v_add3_u32 v170, v170, v173, s96
	v_add3_u32 v171, v171, v172, s96
	v_bfe_u32 v172, v156, 16, 1
	v_bfe_u32 v173, v157, 16, 1
	v_bfe_u32 v174, v160, 16, 1
	v_bfe_u32 v175, v161, 16, 1
	v_or_b32_e32 v154, 16, v169
	v_mov_b64_e32 v[142:143], s[70:71]
	v_add3_u32 v161, v161, v175, s96
	v_add3_u32 v160, v160, v174, s96
	v_add3_u32 v157, v157, v173, s96
	v_add3_u32 v156, v156, v172, s96
	v_mad_i64_i32 v[154:155], s[4:5], v154, s60, v[142:143]
	v_lshrrev_b32_e32 v156, 16, v156
	v_lshrrev_b32_e32 v157, 16, v157
	v_lshrrev_b32_e32 v160, 16, v160
	v_lshrrev_b32_e32 v161, 16, v161
	v_lshl_add_u64 v[154:155], v[154:155], 0, v[152:153]
	v_and_or_b32 v173, v171, s97, v161
	v_and_or_b32 v172, v170, s97, v160
	v_and_or_b32 v171, v159, s97, v157
	v_and_or_b32 v170, v158, s97, v156
	s_waitcnt lgkmcnt(0)
	global_store_dwordx4 v[198:199], v[208:211], off offset:2560
	ds_bpermute_b32 v216, v194, v170
	ds_bpermute_b32 v217, v194, v171
	ds_bpermute_b32 v218, v194, v172
	ds_bpermute_b32 v219, v194, v173
	v_lshl_add_u64 v[240:241], v[154:155], 0, v[196:197]
	v_mul_f32_e32 v155, 0xbfb8aa3b, v92
	v_exp_f32_e32 v156, v155
	v_mul_f32_e32 v155, 0xbfb8aa3b, v93
	v_mul_f32_e32 v158, 0xbfb8aa3b, v94
	v_exp_f32_e32 v157, v155
	v_exp_f32_e32 v159, v158
	v_mul_f32_e32 v158, 0xbfb8aa3b, v95
	v_exp_f32_e32 v160, v158
	v_add_f32_e32 v157, 1.0, v157
	v_mul_f32_e32 v161, 0xbfb8aa3b, v89
	v_rcp_f32_e32 v158, v157
	v_add_f32_e32 v157, 1.0, v159
	v_add_f32_e32 v159, 1.0, v160
	v_mul_f32_e32 v160, 0xbfb8aa3b, v88
	v_exp_f32_e32 v161, v161
	v_mul_f32_e32 v170, 0xbfb8aa3b, v90
	v_exp_f32_e32 v160, v160
	v_exp_f32_e32 v171, v170
	v_mul_f32_e32 v170, 0xbfb8aa3b, v91
	v_exp_f32_e32 v172, v170
	v_add_f32_e32 v156, 1.0, v156
	v_rcp_f32_e32 v156, v156
	v_rcp_f32_e32 v157, v157
	v_add_f32_e32 v161, 1.0, v161
	v_rcp_f32_e32 v159, v159
	v_add_f32_e32 v160, 1.0, v160
	v_rcp_f32_e32 v170, v161
	v_add_f32_e32 v161, 1.0, v171
	v_rcp_f32_e32 v160, v160
	v_rcp_f32_e32 v161, v161
	v_add_f32_e32 v171, 1.0, v172
	v_rcp_f32_e32 v171, v171
	v_mov_b32_e32 v172, v84
	v_mov_b32_e32 v173, v86
	v_pk_mul_f32 v[156:157], v[172:173], v[156:157]
	v_mov_b32_e32 v172, v85
	v_mov_b32_e32 v173, v87
	v_pk_mul_f32 v[158:159], v[172:173], v[158:159]
	v_mov_b32_e32 v172, v80
	v_mov_b32_e32 v173, v82
	v_pk_mul_f32 v[160:161], v[172:173], v[160:161]
	v_mov_b32_e32 v172, v81
	v_mov_b32_e32 v173, v83
	v_pk_mul_f32 v[170:171], v[172:173], v[170:171]
	v_bfe_u32 v174, v159, 16, 1
	v_bfe_u32 v172, v171, 16, 1
	v_bfe_u32 v173, v170, 16, 1
	v_bfe_u32 v175, v158, 16, 1
	v_add3_u32 v158, v158, v175, s96
	v_add3_u32 v159, v159, v174, s96
	v_add3_u32 v170, v170, v173, s96
	v_add3_u32 v171, v171, v172, s96
	v_bfe_u32 v172, v156, 16, 1
	v_bfe_u32 v173, v157, 16, 1
	v_bfe_u32 v174, v160, 16, 1
	v_bfe_u32 v175, v161, 16, 1
	v_or_b32_e32 v154, 32, v169
	v_add3_u32 v161, v161, v175, s96
	v_add3_u32 v160, v160, v174, s96
	v_add3_u32 v157, v157, v173, s96
	v_add3_u32 v156, v156, v172, s96
	v_mad_i64_i32 v[154:155], s[4:5], v154, s60, v[142:143]
	v_lshrrev_b32_e32 v156, 16, v156
	v_lshrrev_b32_e32 v157, 16, v157
	v_lshrrev_b32_e32 v160, 16, v160
	v_lshrrev_b32_e32 v161, 16, v161
	v_lshl_add_u64 v[154:155], v[154:155], 0, v[152:153]
	v_and_or_b32 v173, v171, s97, v161
	v_and_or_b32 v172, v170, s97, v160
	v_and_or_b32 v171, v159, s97, v157
	v_and_or_b32 v170, v158, s97, v156
	s_waitcnt lgkmcnt(0)
	global_store_dwordx4 v[240:241], v[216:219], off offset:2560
	ds_bpermute_b32 v208, v194, v170
	ds_bpermute_b32 v209, v194, v171
	ds_bpermute_b32 v210, v194, v172
	ds_bpermute_b32 v211, v194, v173
	v_lshl_add_u64 v[198:199], v[154:155], 0, v[196:197]
	v_mul_f32_e32 v155, 0xbfb8aa3b, v76
	v_exp_f32_e32 v156, v155
	v_mul_f32_e32 v155, 0xbfb8aa3b, v77
	v_mul_f32_e32 v158, 0xbfb8aa3b, v78
	v_exp_f32_e32 v157, v155
	v_exp_f32_e32 v159, v158
	v_mul_f32_e32 v158, 0xbfb8aa3b, v79
	v_exp_f32_e32 v160, v158
	v_add_f32_e32 v157, 1.0, v157
	v_mul_f32_e32 v161, 0xbfb8aa3b, v73
	v_rcp_f32_e32 v158, v157
	v_add_f32_e32 v157, 1.0, v159
	v_add_f32_e32 v159, 1.0, v160
	v_mul_f32_e32 v160, 0xbfb8aa3b, v72
	v_exp_f32_e32 v161, v161
	v_mul_f32_e32 v170, 0xbfb8aa3b, v74
	v_exp_f32_e32 v160, v160
	v_exp_f32_e32 v171, v170
	v_mul_f32_e32 v170, 0xbfb8aa3b, v75
	v_exp_f32_e32 v172, v170
	v_add_f32_e32 v156, 1.0, v156
	v_rcp_f32_e32 v156, v156
	v_rcp_f32_e32 v157, v157
	v_add_f32_e32 v161, 1.0, v161
	v_rcp_f32_e32 v159, v159
	v_add_f32_e32 v160, 1.0, v160
	v_rcp_f32_e32 v170, v161
	v_add_f32_e32 v161, 1.0, v171
	v_rcp_f32_e32 v160, v160
	v_rcp_f32_e32 v161, v161
	v_add_f32_e32 v171, 1.0, v172
	v_rcp_f32_e32 v171, v171
	v_mov_b32_e32 v172, v68
	v_mov_b32_e32 v173, v70
	v_pk_mul_f32 v[156:157], v[172:173], v[156:157]
	v_mov_b32_e32 v172, v69
	v_mov_b32_e32 v173, v71
	v_pk_mul_f32 v[158:159], v[172:173], v[158:159]
	v_mov_b32_e32 v172, v64
	v_mov_b32_e32 v173, v66
	v_pk_mul_f32 v[160:161], v[172:173], v[160:161]
	v_mov_b32_e32 v172, v65
	v_mov_b32_e32 v173, v67
	v_pk_mul_f32 v[170:171], v[172:173], v[170:171]
	v_bfe_u32 v174, v159, 16, 1
	v_bfe_u32 v172, v171, 16, 1
	v_bfe_u32 v173, v170, 16, 1
	v_bfe_u32 v175, v158, 16, 1
	v_add3_u32 v158, v158, v175, s96
	v_add3_u32 v159, v159, v174, s96
	v_add3_u32 v170, v170, v173, s96
	v_add3_u32 v171, v171, v172, s96
	v_bfe_u32 v172, v156, 16, 1
	v_bfe_u32 v173, v157, 16, 1
	v_bfe_u32 v174, v160, 16, 1
	v_bfe_u32 v175, v161, 16, 1
	v_or_b32_e32 v154, 48, v169
	v_add3_u32 v161, v161, v175, s96
	v_add3_u32 v160, v160, v174, s96
	v_add3_u32 v157, v157, v173, s96
	v_add3_u32 v156, v156, v172, s96
	v_mad_i64_i32 v[154:155], s[4:5], v154, s60, v[142:143]
	v_lshrrev_b32_e32 v156, 16, v156
	v_lshrrev_b32_e32 v157, 16, v157
	v_lshrrev_b32_e32 v160, 16, v160
	v_lshrrev_b32_e32 v161, 16, v161
	v_lshl_add_u64 v[154:155], v[154:155], 0, v[152:153]
	v_and_or_b32 v173, v171, s97, v161
	v_and_or_b32 v172, v170, s97, v160
	v_and_or_b32 v171, v159, s97, v157
	v_and_or_b32 v170, v158, s97, v156
	s_waitcnt lgkmcnt(0)
	global_store_dwordx4 v[198:199], v[208:211], off offset:2560
	ds_bpermute_b32 v216, v194, v170
	ds_bpermute_b32 v217, v194, v171
	ds_bpermute_b32 v218, v194, v172
	ds_bpermute_b32 v219, v194, v173
	v_lshl_add_u64 v[240:241], v[154:155], 0, v[196:197]
	v_mul_f32_e32 v155, 0xbfb8aa3b, v60
	v_exp_f32_e32 v156, v155
	v_mul_f32_e32 v155, 0xbfb8aa3b, v61
	v_mul_f32_e32 v158, 0xbfb8aa3b, v62
	v_exp_f32_e32 v157, v155
	v_exp_f32_e32 v159, v158
	v_mul_f32_e32 v158, 0xbfb8aa3b, v63
	v_exp_f32_e32 v160, v158
	v_add_f32_e32 v157, 1.0, v157
	v_mul_f32_e32 v161, 0xbfb8aa3b, v57
	v_rcp_f32_e32 v158, v157
	v_add_f32_e32 v157, 1.0, v159
	v_add_f32_e32 v159, 1.0, v160
	v_mul_f32_e32 v160, 0xbfb8aa3b, v56
	v_exp_f32_e32 v161, v161
	v_mul_f32_e32 v170, 0xbfb8aa3b, v58
	v_exp_f32_e32 v160, v160
	v_exp_f32_e32 v171, v170
	v_mul_f32_e32 v170, 0xbfb8aa3b, v59
	v_exp_f32_e32 v172, v170
	v_add_f32_e32 v156, 1.0, v156
	v_rcp_f32_e32 v156, v156
	v_rcp_f32_e32 v157, v157
	v_add_f32_e32 v161, 1.0, v161
	v_rcp_f32_e32 v159, v159
	v_add_f32_e32 v160, 1.0, v160
	v_rcp_f32_e32 v170, v161
	v_add_f32_e32 v161, 1.0, v171
	v_rcp_f32_e32 v160, v160
	v_rcp_f32_e32 v161, v161
	v_add_f32_e32 v171, 1.0, v172
	v_rcp_f32_e32 v171, v171
	v_mov_b32_e32 v172, v52
	v_mov_b32_e32 v173, v54
	v_pk_mul_f32 v[156:157], v[172:173], v[156:157]
	v_mov_b32_e32 v172, v53
	v_mov_b32_e32 v173, v55
	v_pk_mul_f32 v[158:159], v[172:173], v[158:159]
	v_mov_b32_e32 v172, v48
	v_mov_b32_e32 v173, v50
	v_pk_mul_f32 v[160:161], v[172:173], v[160:161]
	v_mov_b32_e32 v172, v49
	v_mov_b32_e32 v173, v51
	v_pk_mul_f32 v[170:171], v[172:173], v[170:171]
	v_bfe_u32 v174, v159, 16, 1
	v_bfe_u32 v172, v171, 16, 1
	v_bfe_u32 v173, v170, 16, 1
	v_bfe_u32 v175, v158, 16, 1
	v_add3_u32 v158, v158, v175, s96
	v_add3_u32 v159, v159, v174, s96
	v_add3_u32 v170, v170, v173, s96
	v_add3_u32 v171, v171, v172, s96
	v_bfe_u32 v172, v156, 16, 1
	v_bfe_u32 v173, v157, 16, 1
	v_bfe_u32 v174, v160, 16, 1
	v_bfe_u32 v175, v161, 16, 1
	v_add_u32_e32 v154, 0x80, v169
	v_add3_u32 v161, v161, v175, s96
	v_add3_u32 v160, v160, v174, s96
	v_add3_u32 v157, v157, v173, s96
	v_add3_u32 v156, v156, v172, s96
	v_mad_i64_i32 v[154:155], s[4:5], v154, s60, v[142:143]
	v_lshrrev_b32_e32 v156, 16, v156
	v_lshrrev_b32_e32 v157, 16, v157
	v_lshrrev_b32_e32 v160, 16, v160
	v_lshrrev_b32_e32 v161, 16, v161
	v_lshl_add_u64 v[154:155], v[154:155], 0, v[152:153]
	v_and_or_b32 v173, v171, s97, v161
	v_and_or_b32 v172, v170, s97, v160
	v_and_or_b32 v171, v159, s97, v157
	v_and_or_b32 v170, v158, s97, v156
	s_waitcnt lgkmcnt(0)
	global_store_dwordx4 v[240:241], v[216:219], off offset:2560
	ds_bpermute_b32 v208, v194, v170
	ds_bpermute_b32 v209, v194, v171
	ds_bpermute_b32 v210, v194, v172
	ds_bpermute_b32 v211, v194, v173
	v_lshl_add_u64 v[198:199], v[154:155], 0, v[196:197]
	v_mul_f32_e32 v155, 0xbfb8aa3b, v44
	v_exp_f32_e32 v156, v155
	v_mul_f32_e32 v155, 0xbfb8aa3b, v45
	v_mul_f32_e32 v158, 0xbfb8aa3b, v46
	v_exp_f32_e32 v157, v155
	v_exp_f32_e32 v159, v158
	v_mul_f32_e32 v158, 0xbfb8aa3b, v47
	v_exp_f32_e32 v160, v158
	v_add_f32_e32 v157, 1.0, v157
	v_mul_f32_e32 v161, 0xbfb8aa3b, v41
	v_rcp_f32_e32 v158, v157
	v_add_f32_e32 v157, 1.0, v159
	v_add_f32_e32 v159, 1.0, v160
	v_mul_f32_e32 v160, 0xbfb8aa3b, v40
	v_exp_f32_e32 v161, v161
	v_mul_f32_e32 v170, 0xbfb8aa3b, v42
	v_exp_f32_e32 v160, v160
	v_exp_f32_e32 v171, v170
	v_mul_f32_e32 v170, 0xbfb8aa3b, v43
	v_exp_f32_e32 v172, v170
	v_add_f32_e32 v156, 1.0, v156
	v_rcp_f32_e32 v156, v156
	v_rcp_f32_e32 v157, v157
	v_add_f32_e32 v161, 1.0, v161
	v_rcp_f32_e32 v159, v159
	v_add_f32_e32 v160, 1.0, v160
	v_rcp_f32_e32 v170, v161
	v_add_f32_e32 v161, 1.0, v171
	v_rcp_f32_e32 v160, v160
	v_rcp_f32_e32 v161, v161
	v_add_f32_e32 v171, 1.0, v172
	v_rcp_f32_e32 v171, v171
	v_mov_b32_e32 v172, v36
	v_mov_b32_e32 v173, v38
	v_pk_mul_f32 v[156:157], v[172:173], v[156:157]
	v_mov_b32_e32 v172, v37
	v_mov_b32_e32 v173, v39
	v_pk_mul_f32 v[158:159], v[172:173], v[158:159]
	v_mov_b32_e32 v172, v32
	v_mov_b32_e32 v173, v34
	v_pk_mul_f32 v[160:161], v[172:173], v[160:161]
	v_mov_b32_e32 v172, v33
	v_mov_b32_e32 v173, v35
	v_pk_mul_f32 v[170:171], v[172:173], v[170:171]
	v_bfe_u32 v174, v159, 16, 1
	v_bfe_u32 v172, v171, 16, 1
	v_bfe_u32 v173, v170, 16, 1
	v_bfe_u32 v175, v158, 16, 1
	v_add3_u32 v158, v158, v175, s96
	v_add3_u32 v159, v159, v174, s96
	v_add3_u32 v170, v170, v173, s96
	v_add3_u32 v171, v171, v172, s96
	v_bfe_u32 v172, v156, 16, 1
	v_bfe_u32 v173, v157, 16, 1
	v_bfe_u32 v174, v160, 16, 1
	v_bfe_u32 v175, v161, 16, 1
	v_add_u32_e32 v154, 0x90, v169
	v_add3_u32 v161, v161, v175, s96
	v_add3_u32 v160, v160, v174, s96
	v_add3_u32 v157, v157, v173, s96
	v_add3_u32 v156, v156, v172, s96
	v_mad_i64_i32 v[154:155], s[4:5], v154, s60, v[142:143]
	v_lshrrev_b32_e32 v156, 16, v156
	v_lshrrev_b32_e32 v157, 16, v157
	v_lshrrev_b32_e32 v160, 16, v160
	v_lshrrev_b32_e32 v161, 16, v161
	v_lshl_add_u64 v[154:155], v[154:155], 0, v[152:153]
	v_and_or_b32 v173, v171, s97, v161
	v_and_or_b32 v172, v170, s97, v160
	v_and_or_b32 v171, v159, s97, v157
	v_and_or_b32 v170, v158, s97, v156
	s_waitcnt lgkmcnt(0)
	global_store_dwordx4 v[198:199], v[208:211], off offset:2560
	ds_bpermute_b32 v216, v194, v170
	ds_bpermute_b32 v217, v194, v171
	ds_bpermute_b32 v218, v194, v172
	ds_bpermute_b32 v219, v194, v173
	v_lshl_add_u64 v[240:241], v[154:155], 0, v[196:197]
	v_mul_f32_e32 v155, 0xbfb8aa3b, v28
	v_exp_f32_e32 v156, v155
	v_mul_f32_e32 v155, 0xbfb8aa3b, v29
	v_mul_f32_e32 v158, 0xbfb8aa3b, v30
	v_exp_f32_e32 v157, v155
	v_exp_f32_e32 v159, v158
	v_mul_f32_e32 v158, 0xbfb8aa3b, v31
	v_exp_f32_e32 v160, v158
	v_add_f32_e32 v157, 1.0, v157
	v_mul_f32_e32 v161, 0xbfb8aa3b, v25
	v_rcp_f32_e32 v158, v157
	v_add_f32_e32 v157, 1.0, v159
	v_add_f32_e32 v159, 1.0, v160
	v_mul_f32_e32 v160, 0xbfb8aa3b, v24
	v_exp_f32_e32 v161, v161
	v_mul_f32_e32 v170, 0xbfb8aa3b, v26
	v_exp_f32_e32 v160, v160
	v_exp_f32_e32 v171, v170
	v_mul_f32_e32 v170, 0xbfb8aa3b, v27
	v_exp_f32_e32 v172, v170
	v_add_f32_e32 v156, 1.0, v156
	v_rcp_f32_e32 v156, v156
	v_rcp_f32_e32 v157, v157
	v_add_f32_e32 v161, 1.0, v161
	v_rcp_f32_e32 v159, v159
	v_add_f32_e32 v160, 1.0, v160
	v_rcp_f32_e32 v170, v161
	v_add_f32_e32 v161, 1.0, v171
	v_rcp_f32_e32 v160, v160
	v_rcp_f32_e32 v161, v161
	v_add_f32_e32 v171, 1.0, v172
	v_rcp_f32_e32 v171, v171
	v_mov_b32_e32 v172, v20
	v_mov_b32_e32 v173, v22
	v_pk_mul_f32 v[156:157], v[172:173], v[156:157]
	v_mov_b32_e32 v172, v21
	v_mov_b32_e32 v173, v23
	v_pk_mul_f32 v[158:159], v[172:173], v[158:159]
	v_mov_b32_e32 v172, v16
	v_mov_b32_e32 v173, v18
	v_pk_mul_f32 v[160:161], v[172:173], v[160:161]
	v_mov_b32_e32 v172, v17
	v_mov_b32_e32 v173, v19
	v_pk_mul_f32 v[170:171], v[172:173], v[170:171]
	v_bfe_u32 v174, v159, 16, 1
	v_bfe_u32 v172, v171, 16, 1
	v_bfe_u32 v173, v170, 16, 1
	v_bfe_u32 v175, v158, 16, 1
	v_add3_u32 v158, v158, v175, s96
	v_add3_u32 v159, v159, v174, s96
	v_add3_u32 v170, v170, v173, s96
	v_add3_u32 v171, v171, v172, s96
	v_bfe_u32 v172, v156, 16, 1
	v_bfe_u32 v173, v157, 16, 1
	v_bfe_u32 v174, v160, 16, 1
	v_bfe_u32 v175, v161, 16, 1
	v_add_u32_e32 v154, 0xa0, v169
	v_add3_u32 v161, v161, v175, s96
	v_add3_u32 v160, v160, v174, s96
	v_add3_u32 v157, v157, v173, s96
	v_add3_u32 v156, v156, v172, s96
	v_mad_i64_i32 v[154:155], s[4:5], v154, s60, v[142:143]
	v_lshrrev_b32_e32 v156, 16, v156
	v_lshrrev_b32_e32 v157, 16, v157
	v_lshrrev_b32_e32 v160, 16, v160
	v_lshrrev_b32_e32 v161, 16, v161
	v_lshl_add_u64 v[154:155], v[154:155], 0, v[152:153]
	v_and_or_b32 v173, v171, s97, v161
	v_and_or_b32 v172, v170, s97, v160
	v_and_or_b32 v171, v159, s97, v157
	v_and_or_b32 v170, v158, s97, v156
	s_waitcnt lgkmcnt(0)
	global_store_dwordx4 v[240:241], v[216:219], off offset:2560
	ds_bpermute_b32 v208, v194, v170
	ds_bpermute_b32 v209, v194, v171
	ds_bpermute_b32 v210, v194, v172
	ds_bpermute_b32 v211, v194, v173
	v_lshl_add_u64 v[198:199], v[154:155], 0, v[196:197]
	v_mul_f32_e32 v155, 0xbfb8aa3b, v12
	v_mul_f32_e32 v156, 0xbfb8aa3b, v13
	v_exp_f32_e32 v155, v155
	v_exp_f32_e32 v156, v156
	v_add_u32_e32 v154, 0xb0, v169
	v_mad_i64_i32 v[142:143], s[4:5], v154, s60, v[142:143]
	v_add_f32_e32 v154, 1.0, v155
	v_add_f32_e32 v155, 1.0, v156
	v_mul_f32_e32 v156, 0xbfb8aa3b, v14
	v_exp_f32_e32 v157, v156
	v_mul_f32_e32 v156, 0xbfb8aa3b, v15
	v_exp_f32_e32 v158, v156
	v_mul_f32_e32 v159, 0xbfb8aa3b, v5
	v_rcp_f32_e32 v156, v155
	v_add_f32_e32 v155, 1.0, v157
	v_add_f32_e32 v157, 1.0, v158
	v_mul_f32_e32 v158, 0xbfb8aa3b, v4
	v_exp_f32_e32 v159, v159
	v_mul_f32_e32 v160, 0xbfb8aa3b, v6
	v_exp_f32_e32 v158, v158
	v_exp_f32_e32 v161, v160
	v_mul_f32_e32 v160, 0xbfb8aa3b, v7
	v_exp_f32_e32 v170, v160
	v_rcp_f32_e32 v154, v154
	v_rcp_f32_e32 v155, v155
	v_add_f32_e32 v159, 1.0, v159
	v_rcp_f32_e32 v157, v157
	v_add_f32_e32 v158, 1.0, v158
	v_rcp_f32_e32 v160, v159
	v_add_f32_e32 v159, 1.0, v161
	v_rcp_f32_e32 v158, v158
	v_rcp_f32_e32 v159, v159
	v_add_f32_e32 v161, 1.0, v170
	v_rcp_f32_e32 v161, v161
	v_mov_b32_e32 v170, v8
	v_mov_b32_e32 v171, v10
	v_pk_mul_f32 v[154:155], v[170:171], v[154:155]
	v_mov_b32_e32 v170, v9
	v_mov_b32_e32 v171, v11
	v_pk_mul_f32 v[156:157], v[170:171], v[156:157]
	v_mov_b32_e32 v170, v0
	v_mov_b32_e32 v171, v2
	v_pk_mul_f32 v[158:159], v[170:171], v[158:159]
	v_mov_b32_e32 v170, v1
	v_mov_b32_e32 v171, v3
	v_pk_mul_f32 v[160:161], v[170:171], v[160:161]
	v_lshl_add_u64 v[142:143], v[142:143], 0, v[152:153]
	v_bfe_u32 v152, v161, 16, 1
	v_bfe_u32 v170, v160, 16, 1
	v_bfe_u32 v171, v157, 16, 1
	v_bfe_u32 v172, v156, 16, 1
	v_add3_u32 v156, v156, v172, s96
	v_add3_u32 v157, v157, v171, s96
	v_add3_u32 v160, v160, v170, s96
	v_add3_u32 v152, v161, v152, s96
	v_bfe_u32 v161, v154, 16, 1
	v_bfe_u32 v170, v155, 16, 1
	v_bfe_u32 v171, v158, 16, 1
	v_bfe_u32 v172, v159, 16, 1
	v_add3_u32 v159, v159, v172, s96
	v_add3_u32 v158, v158, v171, s96
	v_add3_u32 v155, v155, v170, s96
	v_add3_u32 v154, v154, v161, s96
	v_lshrrev_b32_e32 v154, 16, v154
	v_lshrrev_b32_e32 v155, 16, v155
	v_lshrrev_b32_e32 v158, 16, v158
	v_lshrrev_b32_e32 v159, 16, v159
	v_and_or_b32 v173, v152, s97, v159
	v_and_or_b32 v172, v160, s97, v158
	v_and_or_b32 v171, v157, s97, v155
	v_and_or_b32 v170, v156, s97, v154
	s_waitcnt lgkmcnt(0)
	global_store_dwordx4 v[198:199], v[208:211], off offset:2560
	ds_bpermute_b32 v216, v194, v170
	ds_bpermute_b32 v217, v194, v171
	ds_bpermute_b32 v218, v194, v172
	ds_bpermute_b32 v219, v194, v173
	v_lshl_add_u64 v[240:241], v[142:143], 0, v[196:197]
	s_waitcnt lgkmcnt(0)
	global_store_dwordx4 v[240:241], v[216:219], off offset:2560
	s_mov_b64 s[4:5], 0
.LBB0_481:
	s_andn2_b64 vcc, exec, s[4:5]
	s_cbranch_vccnz .LBB0_483
	v_lshl_or_b32 v152, s35, 9, v168
	v_lshl_add_u64 v[154:155], v[140:141], 0, v[152:153]
	v_bfe_u32 v140, v116, 16, 1
	v_add3_u32 v140, v116, v140, s96
	v_bfe_u32 v141, v117, 16, 1
	v_lshrrev_b32_e32 v140, 16, v140
	v_add3_u32 v141, v117, v141, s96
	v_and_or_b32 v140, v141, s97, v140
	v_bfe_u32 v141, v118, 16, 1
	v_add3_u32 v141, v118, v141, s96
	v_bfe_u32 v142, v119, 16, 1
	v_lshrrev_b32_e32 v141, 16, v141
	v_add3_u32 v142, v119, v142, s96
	v_and_or_b32 v141, v142, s97, v141
	v_bfe_u32 v142, v112, 16, 1
	v_add3_u32 v142, v112, v142, s96
	v_bfe_u32 v143, v113, 16, 1
	v_lshrrev_b32_e32 v142, 16, v142
	v_add3_u32 v143, v113, v143, s96
	v_and_or_b32 v142, v143, s97, v142
	v_bfe_u32 v143, v114, 16, 1
	v_add3_u32 v143, v114, v143, s96
	v_bfe_u32 v156, v115, 16, 1
	v_lshrrev_b32_e32 v143, 16, v143
	v_add3_u32 v156, v115, v156, s96
	v_and_or_b32 v143, v156, s97, v143
	ds_bpermute_b32 v208, v194, v140
	ds_bpermute_b32 v209, v194, v141
	ds_bpermute_b32 v210, v194, v142
	ds_bpermute_b32 v211, v194, v143
	v_lshl_add_u64 v[198:199], v[154:155], 0, v[196:197]
	v_bfe_u32 v156, v123, 16, 1
	v_add3_u32 v156, v123, v156, s96
	v_bfe_u32 v140, v124, 16, 1
	v_add3_u32 v140, v124, v140, s96
	v_bfe_u32 v141, v125, 16, 1
	v_lshrrev_b32_e32 v140, 16, v140
	v_add3_u32 v141, v125, v141, s96
	v_and_or_b32 v140, v141, s97, v140
	v_bfe_u32 v141, v126, 16, 1
	v_add3_u32 v141, v126, v141, s96
	v_bfe_u32 v142, v127, 16, 1
	v_lshrrev_b32_e32 v141, 16, v141
	v_add3_u32 v142, v127, v142, s96
	v_and_or_b32 v141, v142, s97, v141
	v_bfe_u32 v142, v120, 16, 1
	v_add3_u32 v142, v120, v142, s96
	v_bfe_u32 v143, v121, 16, 1
	v_lshrrev_b32_e32 v142, 16, v142
	v_add3_u32 v143, v121, v143, s96
	v_and_or_b32 v142, v143, s97, v142
	v_bfe_u32 v143, v122, 16, 1
	v_add3_u32 v143, v122, v143, s96
	v_lshrrev_b32_e32 v143, 16, v143
	v_and_or_b32 v143, v156, s97, v143
	s_waitcnt lgkmcnt(0)
	global_store_dwordx4 v[198:199], v[208:211], off
	ds_bpermute_b32 v216, v194, v140
	ds_bpermute_b32 v217, v194, v141
	ds_bpermute_b32 v218, v194, v142
	ds_bpermute_b32 v219, v194, v143
	v_lshl_add_u64 v[240:241], v[154:155], 0, v[196:197]
	v_bfe_u32 v154, v100, 16, 1
	v_add3_u32 v154, v100, v154, s96
	v_bfe_u32 v155, v101, 16, 1
	v_lshrrev_b32_e32 v154, 16, v154
	v_add3_u32 v155, v101, v155, s96
	v_and_or_b32 v170, v155, s97, v154
	v_bfe_u32 v154, v102, 16, 1
	v_add3_u32 v154, v102, v154, s96
	v_bfe_u32 v155, v103, 16, 1
	v_lshrrev_b32_e32 v154, 16, v154
	v_add3_u32 v155, v103, v155, s96
	v_and_or_b32 v171, v155, s97, v154
	v_bfe_u32 v154, v96, 16, 1
	v_add3_u32 v154, v96, v154, s96
	v_bfe_u32 v155, v97, 16, 1
	v_lshrrev_b32_e32 v154, 16, v154
	v_add3_u32 v155, v97, v155, s96
	v_and_or_b32 v172, v155, s97, v154
	v_bfe_u32 v154, v98, 16, 1
	v_add3_u32 v154, v98, v154, s96
	v_bfe_u32 v155, v99, 16, 1
	v_lshrrev_b32_e32 v154, 16, v154
	v_add3_u32 v155, v99, v155, s96
	v_or_b32_e32 v142, 16, v169
	v_mov_b64_e32 v[140:141], s[70:71]
	v_and_or_b32 v173, v155, s97, v154
	v_bfe_u32 v154, v108, 16, 1
	v_mad_i64_i32 v[142:143], s[4:5], v142, s60, v[140:141]
	v_add3_u32 v154, v108, v154, s96
	v_bfe_u32 v155, v109, 16, 1
	v_lshl_add_u64 v[142:143], v[142:143], 0, v[152:153]
	v_lshrrev_b32_e32 v154, 16, v154
	v_add3_u32 v155, v109, v155, s96
	s_waitcnt lgkmcnt(0)
	global_store_dwordx4 v[240:241], v[216:219], off offset:256
	ds_bpermute_b32 v208, v194, v170
	ds_bpermute_b32 v209, v194, v171
	ds_bpermute_b32 v210, v194, v172
	ds_bpermute_b32 v211, v194, v173
	v_lshl_add_u64 v[198:199], v[142:143], 0, v[196:197]
	s_nop 1
	v_and_or_b32 v170, v155, s97, v154
	v_bfe_u32 v154, v110, 16, 1
	v_add3_u32 v154, v110, v154, s96
	v_bfe_u32 v155, v111, 16, 1
	v_lshrrev_b32_e32 v154, 16, v154
	v_add3_u32 v155, v111, v155, s96
	v_and_or_b32 v171, v155, s97, v154
	v_bfe_u32 v154, v104, 16, 1
	v_add3_u32 v154, v104, v154, s96
	v_bfe_u32 v155, v105, 16, 1
	v_lshrrev_b32_e32 v154, 16, v154
	v_add3_u32 v155, v105, v155, s96
	v_and_or_b32 v172, v155, s97, v154
	v_bfe_u32 v154, v106, 16, 1
	v_add3_u32 v154, v106, v154, s96
	v_bfe_u32 v155, v107, 16, 1
	v_lshrrev_b32_e32 v154, 16, v154
	v_add3_u32 v155, v107, v155, s96
	v_and_or_b32 v173, v155, s97, v154
	v_bfe_u32 v154, v84, 16, 1
	v_add3_u32 v154, v84, v154, s96
	v_bfe_u32 v155, v85, 16, 1
	v_lshrrev_b32_e32 v154, 16, v154
	v_add3_u32 v155, v85, v155, s96
	s_waitcnt lgkmcnt(0)
	global_store_dwordx4 v[198:199], v[208:211], off
	ds_bpermute_b32 v216, v194, v170
	ds_bpermute_b32 v217, v194, v171
	ds_bpermute_b32 v218, v194, v172
	ds_bpermute_b32 v219, v194, v173
	v_lshl_add_u64 v[240:241], v[142:143], 0, v[196:197]
	v_or_b32_e32 v142, 32, v169
	v_mad_i64_i32 v[142:143], s[4:5], v142, s60, v[140:141]
	v_and_or_b32 v170, v155, s97, v154
	v_bfe_u32 v154, v86, 16, 1
	v_add3_u32 v154, v86, v154, s96
	v_bfe_u32 v155, v87, 16, 1
	v_lshrrev_b32_e32 v154, 16, v154
	v_add3_u32 v155, v87, v155, s96
	v_and_or_b32 v171, v155, s97, v154
	v_bfe_u32 v154, v80, 16, 1
	v_add3_u32 v154, v80, v154, s96
	v_bfe_u32 v155, v81, 16, 1
	v_lshrrev_b32_e32 v154, 16, v154
	v_add3_u32 v155, v81, v155, s96
	v_and_or_b32 v172, v155, s97, v154
	v_bfe_u32 v154, v82, 16, 1
	v_add3_u32 v154, v82, v154, s96
	v_bfe_u32 v155, v83, 16, 1
	v_lshrrev_b32_e32 v154, 16, v154
	v_add3_u32 v155, v83, v155, s96
	v_and_or_b32 v173, v155, s97, v154
	v_bfe_u32 v154, v92, 16, 1
	v_add3_u32 v154, v92, v154, s96
	v_bfe_u32 v155, v93, 16, 1
	v_lshl_add_u64 v[142:143], v[142:143], 0, v[152:153]
	v_lshrrev_b32_e32 v154, 16, v154
	v_add3_u32 v155, v93, v155, s96
	s_waitcnt lgkmcnt(0)
	global_store_dwordx4 v[240:241], v[216:219], off offset:256
	ds_bpermute_b32 v208, v194, v170
	ds_bpermute_b32 v209, v194, v171
	ds_bpermute_b32 v210, v194, v172
	ds_bpermute_b32 v211, v194, v173
	v_lshl_add_u64 v[198:199], v[142:143], 0, v[196:197]
	s_nop 1
	v_and_or_b32 v170, v155, s97, v154
	v_bfe_u32 v154, v94, 16, 1
	v_add3_u32 v154, v94, v154, s96
	v_bfe_u32 v155, v95, 16, 1
	v_lshrrev_b32_e32 v154, 16, v154
	v_add3_u32 v155, v95, v155, s96
	v_and_or_b32 v171, v155, s97, v154
	v_bfe_u32 v154, v88, 16, 1
	v_add3_u32 v154, v88, v154, s96
	v_bfe_u32 v155, v89, 16, 1
	v_lshrrev_b32_e32 v154, 16, v154
	v_add3_u32 v155, v89, v155, s96
	v_and_or_b32 v172, v155, s97, v154
	v_bfe_u32 v154, v90, 16, 1
	v_add3_u32 v154, v90, v154, s96
	v_bfe_u32 v155, v91, 16, 1
	v_lshrrev_b32_e32 v154, 16, v154
	v_add3_u32 v155, v91, v155, s96
	v_and_or_b32 v173, v155, s97, v154
	v_bfe_u32 v154, v68, 16, 1
	v_add3_u32 v154, v68, v154, s96
	v_bfe_u32 v155, v69, 16, 1
	v_lshrrev_b32_e32 v154, 16, v154
	v_add3_u32 v155, v69, v155, s96
	s_waitcnt lgkmcnt(0)
	global_store_dwordx4 v[198:199], v[208:211], off
	ds_bpermute_b32 v216, v194, v170
	ds_bpermute_b32 v217, v194, v171
	ds_bpermute_b32 v218, v194, v172
	ds_bpermute_b32 v219, v194, v173
	v_lshl_add_u64 v[240:241], v[142:143], 0, v[196:197]
	v_or_b32_e32 v142, 48, v169
	v_mad_i64_i32 v[142:143], s[4:5], v142, s60, v[140:141]
	v_and_or_b32 v170, v155, s97, v154
	v_bfe_u32 v154, v70, 16, 1
	v_add3_u32 v154, v70, v154, s96
	v_bfe_u32 v155, v71, 16, 1
	v_lshrrev_b32_e32 v154, 16, v154
	v_add3_u32 v155, v71, v155, s96
	v_and_or_b32 v171, v155, s97, v154
	v_bfe_u32 v154, v64, 16, 1
	v_add3_u32 v154, v64, v154, s96
	v_bfe_u32 v155, v65, 16, 1
	v_lshrrev_b32_e32 v154, 16, v154
	v_add3_u32 v155, v65, v155, s96
	v_and_or_b32 v172, v155, s97, v154
	v_bfe_u32 v154, v66, 16, 1
	v_add3_u32 v154, v66, v154, s96
	v_bfe_u32 v155, v67, 16, 1
	v_lshrrev_b32_e32 v154, 16, v154
	v_add3_u32 v155, v67, v155, s96
	v_and_or_b32 v173, v155, s97, v154
	v_bfe_u32 v154, v76, 16, 1
	v_add3_u32 v154, v76, v154, s96
	v_bfe_u32 v155, v77, 16, 1
	v_lshl_add_u64 v[142:143], v[142:143], 0, v[152:153]
	v_lshrrev_b32_e32 v154, 16, v154
	v_add3_u32 v155, v77, v155, s96
	s_waitcnt lgkmcnt(0)
	global_store_dwordx4 v[240:241], v[216:219], off offset:256
	ds_bpermute_b32 v208, v194, v170
	ds_bpermute_b32 v209, v194, v171
	ds_bpermute_b32 v210, v194, v172
	ds_bpermute_b32 v211, v194, v173
	v_lshl_add_u64 v[198:199], v[142:143], 0, v[196:197]
	s_nop 1
	v_and_or_b32 v170, v155, s97, v154
	v_bfe_u32 v154, v78, 16, 1
	v_add3_u32 v154, v78, v154, s96
	v_bfe_u32 v155, v79, 16, 1
	v_lshrrev_b32_e32 v154, 16, v154
	v_add3_u32 v155, v79, v155, s96
	v_and_or_b32 v171, v155, s97, v154
	v_bfe_u32 v154, v72, 16, 1
	v_add3_u32 v154, v72, v154, s96
	v_bfe_u32 v155, v73, 16, 1
	v_lshrrev_b32_e32 v154, 16, v154
	v_add3_u32 v155, v73, v155, s96
	v_and_or_b32 v172, v155, s97, v154
	v_bfe_u32 v154, v74, 16, 1
	v_add3_u32 v154, v74, v154, s96
	v_bfe_u32 v155, v75, 16, 1
	v_lshrrev_b32_e32 v154, 16, v154
	v_add3_u32 v155, v75, v155, s96
	v_and_or_b32 v173, v155, s97, v154
	v_bfe_u32 v154, v52, 16, 1
	v_add3_u32 v154, v52, v154, s96
	v_bfe_u32 v155, v53, 16, 1
	v_lshrrev_b32_e32 v154, 16, v154
	v_add3_u32 v155, v53, v155, s96
	s_waitcnt lgkmcnt(0)
	global_store_dwordx4 v[198:199], v[208:211], off
	ds_bpermute_b32 v216, v194, v170
	ds_bpermute_b32 v217, v194, v171
	ds_bpermute_b32 v218, v194, v172
	ds_bpermute_b32 v219, v194, v173
	v_lshl_add_u64 v[240:241], v[142:143], 0, v[196:197]
	v_add_u32_e32 v142, 0x80, v169
	v_mad_i64_i32 v[142:143], s[4:5], v142, s60, v[140:141]
	v_and_or_b32 v170, v155, s97, v154
	v_bfe_u32 v154, v54, 16, 1
	v_add3_u32 v154, v54, v154, s96
	v_bfe_u32 v155, v55, 16, 1
	v_lshrrev_b32_e32 v154, 16, v154
	v_add3_u32 v155, v55, v155, s96
	v_and_or_b32 v171, v155, s97, v154
	v_bfe_u32 v154, v48, 16, 1
	v_add3_u32 v154, v48, v154, s96
	v_bfe_u32 v155, v49, 16, 1
	v_lshrrev_b32_e32 v154, 16, v154
	v_add3_u32 v155, v49, v155, s96
	v_and_or_b32 v172, v155, s97, v154
	v_bfe_u32 v154, v50, 16, 1
	v_add3_u32 v154, v50, v154, s96
	v_bfe_u32 v155, v51, 16, 1
	v_lshrrev_b32_e32 v154, 16, v154
	v_add3_u32 v155, v51, v155, s96
	v_and_or_b32 v173, v155, s97, v154
	v_bfe_u32 v154, v60, 16, 1
	v_add3_u32 v154, v60, v154, s96
	v_bfe_u32 v155, v61, 16, 1
	v_lshl_add_u64 v[142:143], v[142:143], 0, v[152:153]
	v_lshrrev_b32_e32 v154, 16, v154
	v_add3_u32 v155, v61, v155, s96
	s_waitcnt lgkmcnt(0)
	global_store_dwordx4 v[240:241], v[216:219], off offset:256
	ds_bpermute_b32 v208, v194, v170
	ds_bpermute_b32 v209, v194, v171
	ds_bpermute_b32 v210, v194, v172
	ds_bpermute_b32 v211, v194, v173
	v_lshl_add_u64 v[198:199], v[142:143], 0, v[196:197]
	s_nop 1
	v_and_or_b32 v170, v155, s97, v154
	v_bfe_u32 v154, v62, 16, 1
	v_add3_u32 v154, v62, v154, s96
	v_bfe_u32 v155, v63, 16, 1
	v_lshrrev_b32_e32 v154, 16, v154
	v_add3_u32 v155, v63, v155, s96
	v_and_or_b32 v171, v155, s97, v154
	v_bfe_u32 v154, v56, 16, 1
	v_add3_u32 v154, v56, v154, s96
	v_bfe_u32 v155, v57, 16, 1
	v_lshrrev_b32_e32 v154, 16, v154
	v_add3_u32 v155, v57, v155, s96
	v_and_or_b32 v172, v155, s97, v154
	v_bfe_u32 v154, v58, 16, 1
	v_add3_u32 v154, v58, v154, s96
	v_bfe_u32 v155, v59, 16, 1
	v_lshrrev_b32_e32 v154, 16, v154
	v_add3_u32 v155, v59, v155, s96
	v_and_or_b32 v173, v155, s97, v154
	v_bfe_u32 v154, v36, 16, 1
	v_add3_u32 v154, v36, v154, s96
	v_bfe_u32 v155, v37, 16, 1
	v_lshrrev_b32_e32 v154, 16, v154
	v_add3_u32 v155, v37, v155, s96
	s_waitcnt lgkmcnt(0)
	global_store_dwordx4 v[198:199], v[208:211], off
	ds_bpermute_b32 v216, v194, v170
	ds_bpermute_b32 v217, v194, v171
	ds_bpermute_b32 v218, v194, v172
	ds_bpermute_b32 v219, v194, v173
	v_lshl_add_u64 v[240:241], v[142:143], 0, v[196:197]
	v_add_u32_e32 v142, 0x90, v169
	v_mad_i64_i32 v[142:143], s[4:5], v142, s60, v[140:141]
	v_and_or_b32 v170, v155, s97, v154
	v_bfe_u32 v154, v38, 16, 1
	v_add3_u32 v154, v38, v154, s96
	v_bfe_u32 v155, v39, 16, 1
	v_lshrrev_b32_e32 v154, 16, v154
	v_add3_u32 v155, v39, v155, s96
	v_and_or_b32 v171, v155, s97, v154
	v_bfe_u32 v154, v32, 16, 1
	v_add3_u32 v154, v32, v154, s96
	v_bfe_u32 v155, v33, 16, 1
	v_lshrrev_b32_e32 v154, 16, v154
	v_add3_u32 v155, v33, v155, s96
	v_and_or_b32 v172, v155, s97, v154
	v_bfe_u32 v154, v34, 16, 1
	v_add3_u32 v154, v34, v154, s96
	v_bfe_u32 v155, v35, 16, 1
	v_lshrrev_b32_e32 v154, 16, v154
	v_add3_u32 v155, v35, v155, s96
	v_and_or_b32 v173, v155, s97, v154
	v_bfe_u32 v154, v44, 16, 1
	v_add3_u32 v154, v44, v154, s96
	v_bfe_u32 v155, v45, 16, 1
	v_lshl_add_u64 v[142:143], v[142:143], 0, v[152:153]
	v_lshrrev_b32_e32 v154, 16, v154
	v_add3_u32 v155, v45, v155, s96
	s_waitcnt lgkmcnt(0)
	global_store_dwordx4 v[240:241], v[216:219], off offset:256
	ds_bpermute_b32 v208, v194, v170
	ds_bpermute_b32 v209, v194, v171
	ds_bpermute_b32 v210, v194, v172
	ds_bpermute_b32 v211, v194, v173
	v_lshl_add_u64 v[198:199], v[142:143], 0, v[196:197]
	s_nop 1
	v_and_or_b32 v170, v155, s97, v154
	v_bfe_u32 v154, v46, 16, 1
	v_add3_u32 v154, v46, v154, s96
	v_bfe_u32 v155, v47, 16, 1
	v_lshrrev_b32_e32 v154, 16, v154
	v_add3_u32 v155, v47, v155, s96
	v_and_or_b32 v171, v155, s97, v154
	v_bfe_u32 v154, v40, 16, 1
	v_add3_u32 v154, v40, v154, s96
	v_bfe_u32 v155, v41, 16, 1
	v_lshrrev_b32_e32 v154, 16, v154
	v_add3_u32 v155, v41, v155, s96
	v_and_or_b32 v172, v155, s97, v154
	v_bfe_u32 v154, v42, 16, 1
	v_add3_u32 v154, v42, v154, s96
	v_bfe_u32 v155, v43, 16, 1
	v_lshrrev_b32_e32 v154, 16, v154
	v_add3_u32 v155, v43, v155, s96
	v_and_or_b32 v173, v155, s97, v154
	v_bfe_u32 v154, v20, 16, 1
	v_add3_u32 v154, v20, v154, s96
	v_bfe_u32 v155, v21, 16, 1
	v_lshrrev_b32_e32 v154, 16, v154
	v_add3_u32 v155, v21, v155, s96
	s_waitcnt lgkmcnt(0)
	global_store_dwordx4 v[198:199], v[208:211], off
	ds_bpermute_b32 v216, v194, v170
	ds_bpermute_b32 v217, v194, v171
	ds_bpermute_b32 v218, v194, v172
	ds_bpermute_b32 v219, v194, v173
	v_lshl_add_u64 v[240:241], v[142:143], 0, v[196:197]
	v_add_u32_e32 v142, 0xa0, v169
	v_mad_i64_i32 v[142:143], s[4:5], v142, s60, v[140:141]
	v_and_or_b32 v170, v155, s97, v154
	v_bfe_u32 v154, v22, 16, 1
	v_add3_u32 v154, v22, v154, s96
	v_bfe_u32 v155, v23, 16, 1
	v_lshrrev_b32_e32 v154, 16, v154
	v_add3_u32 v155, v23, v155, s96
	v_and_or_b32 v171, v155, s97, v154
	v_bfe_u32 v154, v16, 16, 1
	v_add3_u32 v154, v16, v154, s96
	v_bfe_u32 v155, v17, 16, 1
	v_lshrrev_b32_e32 v154, 16, v154
	v_add3_u32 v155, v17, v155, s96
	v_and_or_b32 v172, v155, s97, v154
	v_bfe_u32 v154, v18, 16, 1
	v_add3_u32 v154, v18, v154, s96
	v_bfe_u32 v155, v19, 16, 1
	v_lshrrev_b32_e32 v154, 16, v154
	v_add3_u32 v155, v19, v155, s96
	v_and_or_b32 v173, v155, s97, v154
	v_bfe_u32 v154, v28, 16, 1
	v_add3_u32 v154, v28, v154, s96
	v_bfe_u32 v155, v29, 16, 1
	v_lshl_add_u64 v[142:143], v[142:143], 0, v[152:153]
	v_lshrrev_b32_e32 v154, 16, v154
	v_add3_u32 v155, v29, v155, s96
	s_waitcnt lgkmcnt(0)
	global_store_dwordx4 v[240:241], v[216:219], off offset:256
	ds_bpermute_b32 v208, v194, v170
	ds_bpermute_b32 v209, v194, v171
	ds_bpermute_b32 v210, v194, v172
	ds_bpermute_b32 v211, v194, v173
	v_lshl_add_u64 v[198:199], v[142:143], 0, v[196:197]
	s_nop 1
	v_and_or_b32 v170, v155, s97, v154
	v_bfe_u32 v154, v30, 16, 1
	v_add3_u32 v154, v30, v154, s96
	v_bfe_u32 v155, v31, 16, 1
	v_lshrrev_b32_e32 v154, 16, v154
	v_add3_u32 v155, v31, v155, s96
	v_and_or_b32 v171, v155, s97, v154
	v_bfe_u32 v154, v24, 16, 1
	v_add3_u32 v154, v24, v154, s96
	v_bfe_u32 v155, v25, 16, 1
	v_lshrrev_b32_e32 v154, 16, v154
	v_add3_u32 v155, v25, v155, s96
	v_and_or_b32 v172, v155, s97, v154
	v_bfe_u32 v154, v26, 16, 1
	v_add3_u32 v154, v26, v154, s96
	v_bfe_u32 v155, v27, 16, 1
	v_lshrrev_b32_e32 v154, 16, v154
	v_add3_u32 v155, v27, v155, s96
	v_and_or_b32 v173, v155, s97, v154
	s_waitcnt lgkmcnt(0)
	global_store_dwordx4 v[198:199], v[208:211], off
	ds_bpermute_b32 v216, v194, v170
	ds_bpermute_b32 v217, v194, v171
	ds_bpermute_b32 v218, v194, v172
	ds_bpermute_b32 v219, v194, v173
	v_lshl_add_u64 v[240:241], v[142:143], 0, v[196:197]
	v_add_u32_e32 v142, 0xb0, v169
	v_mad_i64_i32 v[140:141], s[4:5], v142, s60, v[140:141]
	v_lshl_add_u64 v[154:155], v[140:141], 0, v[152:153]
	v_bfe_u32 v140, v8, 16, 1
	v_add3_u32 v140, v8, v140, s96
	v_bfe_u32 v141, v9, 16, 1
	v_lshrrev_b32_e32 v140, 16, v140
	v_add3_u32 v141, v9, v141, s96
	v_and_or_b32 v140, v141, s97, v140
	v_bfe_u32 v141, v10, 16, 1
	v_add3_u32 v141, v10, v141, s96
	v_bfe_u32 v142, v11, 16, 1
	v_lshrrev_b32_e32 v141, 16, v141
	v_add3_u32 v142, v11, v142, s96
	v_and_or_b32 v141, v142, s97, v141
	v_bfe_u32 v142, v0, 16, 1
	v_add3_u32 v142, v0, v142, s96
	v_bfe_u32 v143, v1, 16, 1
	v_lshrrev_b32_e32 v142, 16, v142
	v_add3_u32 v143, v1, v143, s96
	v_and_or_b32 v142, v143, s97, v142
	v_bfe_u32 v143, v2, 16, 1
	v_add3_u32 v143, v2, v143, s96
	v_bfe_u32 v152, v3, 16, 1
	v_lshrrev_b32_e32 v143, 16, v143
	v_add3_u32 v152, v3, v152, s96
	v_and_or_b32 v143, v152, s97, v143
	s_waitcnt lgkmcnt(0)
	global_store_dwordx4 v[240:241], v[216:219], off offset:256
	ds_bpermute_b32 v208, v194, v140
	ds_bpermute_b32 v209, v194, v141
	ds_bpermute_b32 v210, v194, v142
	ds_bpermute_b32 v211, v194, v143
	v_lshl_add_u64 v[198:199], v[154:155], 0, v[196:197]
	v_bfe_u32 v152, v7, 16, 1
	v_add3_u32 v152, v7, v152, s96
	v_bfe_u32 v140, v12, 16, 1
	v_add3_u32 v140, v12, v140, s96
	v_bfe_u32 v141, v13, 16, 1
	v_lshrrev_b32_e32 v140, 16, v140
	v_add3_u32 v141, v13, v141, s96
	v_and_or_b32 v140, v141, s97, v140
	v_bfe_u32 v141, v14, 16, 1
	v_add3_u32 v141, v14, v141, s96
	v_bfe_u32 v142, v15, 16, 1
	v_lshrrev_b32_e32 v141, 16, v141
	v_add3_u32 v142, v15, v142, s96
	v_and_or_b32 v141, v142, s97, v141
	v_bfe_u32 v142, v4, 16, 1
	v_add3_u32 v142, v4, v142, s96
	v_bfe_u32 v143, v5, 16, 1
	v_lshrrev_b32_e32 v142, 16, v142
	v_add3_u32 v143, v5, v143, s96
	v_and_or_b32 v142, v143, s97, v142
	v_bfe_u32 v143, v6, 16, 1
	v_add3_u32 v143, v6, v143, s96
	v_lshrrev_b32_e32 v143, 16, v143
	v_and_or_b32 v143, v152, s97, v143
	s_waitcnt lgkmcnt(0)
	global_store_dwordx4 v[198:199], v[208:211], off
	ds_bpermute_b32 v216, v194, v140
	ds_bpermute_b32 v217, v194, v141
	ds_bpermute_b32 v218, v194, v142
	ds_bpermute_b32 v219, v194, v143
	v_lshl_add_u64 v[240:241], v[154:155], 0, v[196:197]
	s_waitcnt lgkmcnt(0)
	global_store_dwordx4 v[240:241], v[216:219], off offset:256
